# v22: v19 (scan scalar addressing) + conv_s2 trip-2 input loads issued during trip 1 + conv_p barriers sunk below their staging loads
# speedup vs baseline: 1.0037x; 1.0037x over previous
; template <int R> FFT_HD inline void reg_fwd(cf2 (&v)[1 << R], cf2 th) { dft_fwd_reg<R>(v); tw_apply<R, 1, false>(v, th, th); }
; __device__ __forceinline__ void hyena_conv_s2(const float* HYT, float* ZOUT, const float* FILT, const cf2* TW, LAS unsigned char* lds, int vb, int nb, int tid_in) {
;     ...
;         for (int q = 0; q < 2; ++q) { const int grp = tid + 512 * q; cf2 v[16];
; #pragma unroll
;             for (int m = 0; m < 16; ++m) { v[m].x = m < 8 ? hv[grp + 1024 * m] : 0.f; v[m].y = f0[grp + 1024 * m]; }
;             reg_fwd<4>(v, TW[grp]); grp_store<4, 1024>(X, grp, v); }
.LBB0_637:
	s_and_b64 vcc, exec, s[54:55]
	s_cbranch_vccz .Lcs2_a2
	v_cndmask_b32_e64 v2, 0, 1, s[54:55]
	v_cmp_ne_u32_e64 s[4:5], 1, v2
	v_add_u32_e32 v2, s3, v172
	v_ashrrev_i32_e32 v3, 31, v2
	v_lshlrev_b64 v[6:7], 2, v[2:3]
	v_lshl_add_u64 v[14:15], s[42:43], 0, v[6:7]
	v_add_co_u32_e32 v8, vcc, 0x1000, v14
	v_lshl_add_u64 v[6:7], s[50:51], 0, v[6:7]
	s_nop 0
	v_addc_co_u32_e32 v9, vcc, 0, v15, vcc
	global_load_dword v200, v[14:15], off offset:2048
	global_load_dword v4, v[14:15], off
	global_load_dword v201, v[6:7], off offset:2048
	global_load_dword v29, v[6:7], off
	global_load_dword v202, v[8:9], off offset:2048
	global_load_dword v10, v[8:9], off
	v_add_co_u32_e32 v8, vcc, 0x1000, v6
	s_mov_b32 s26, s61
	s_nop 0
	v_addc_co_u32_e32 v9, vcc, 0, v7, vcc
	global_load_dword v203, v[8:9], off offset:2048
	global_load_dword v32, v[8:9], off
	v_add_co_u32_e32 v8, vcc, s48, v14
	s_mov_b32 s27, s60
	s_nop 0
	v_addc_co_u32_e32 v9, vcc, 0, v15, vcc
	global_load_dword v204, v[8:9], off offset:2048
	global_load_dword v30, v[8:9], off
	v_add_co_u32_e32 v8, vcc, s48, v6
	s_mov_b32 s79, s61
	s_nop 0
	v_addc_co_u32_e32 v9, vcc, 0, v7, vcc
	global_load_dword v205, v[8:9], off offset:2048
	global_load_dword v35, v[8:9], off
	v_add_co_u32_e32 v8, vcc, 0x3000, v14
	s_mov_b32 s30, s80
	s_nop 0
	v_addc_co_u32_e32 v9, vcc, 0, v15, vcc
	global_load_dword v206, v[8:9], off offset:2048
	global_load_dword v31, v[8:9], off
	v_add_co_u32_e32 v8, vcc, 0x3000, v6
	s_mov_b32 s31, s60
	s_nop 0
	v_addc_co_u32_e32 v9, vcc, 0, v7, vcc
	v_add_co_u32_e32 v12, vcc, s40, v14
	global_load_dword v207, v[8:9], off offset:2048
	global_load_dword v34, v[8:9], off
	s_nop 0
	v_addc_co_u32_e32 v13, vcc, 0, v15, vcc
	v_add_co_u32_e32 v16, vcc, s40, v6
	global_load_dword v208, v[12:13], off offset:-2048
	global_load_dword v8, v[12:13], off offset:-4096
	s_nop 0
	v_addc_co_u32_e32 v17, vcc, 0, v7, vcc
	v_add_co_u32_e32 v14, vcc, s33, v14
	global_load_dword v209, v[16:17], off offset:-2048
	global_load_dword v19, v[16:17], off offset:-4096
	s_nop 0
	global_load_dword v210, v[12:13], off offset:2048
	global_load_dword v13, v[12:13], off
	s_nop 0
	global_load_dword v211, v[16:17], off offset:2048
	global_load_dword v18, v[16:17], off
	v_addc_co_u32_e32 v15, vcc, 0, v15, vcc
	v_add_co_u32_e32 v22, vcc, s33, v6
	global_load_dword v212, v[14:15], off offset:-2048
	global_load_dword v16, v[14:15], off offset:-4096
	s_nop 0
	v_addc_co_u32_e32 v23, vcc, 0, v7, vcc
	global_load_dword v213, v[22:23], off offset:-2048
	global_load_dword v21, v[22:23], off offset:-4096
	global_load_dword v214, v[14:15], off offset:2048
	global_load_dword v17, v[14:15], off
	global_load_dword v215, v[22:23], off offset:2048
	global_load_dword v20, v[22:23], off
	v_add_co_u32_e32 v14, vcc, s1, v6
	s_mov_b32 s28, s80
	s_nop 0
	v_addc_co_u32_e32 v15, vcc, 0, v7, vcc
	global_load_dword v236, v[14:15], off offset:-2048
	global_load_dword v33, v[14:15], off offset:-4096
	global_load_dword v237, v[14:15], off offset:2048
	global_load_dword v28, v[14:15], off
	v_add_co_u32_e32 v14, vcc, s92, v6
	s_mov_b32 s29, s61
	s_nop 0
	v_addc_co_u32_e32 v15, vcc, 0, v7, vcc
	global_load_dword v238, v[14:15], off offset:-2048
	global_load_dword v45, v[14:15], off offset:-4096
	global_load_dword v239, v[14:15], off offset:2048
	global_load_dword v44, v[14:15], off
	v_add_co_u32_e32 v14, vcc, s0, v6
	s_mov_b32 s44, s61
	s_nop 0
	v_addc_co_u32_e32 v15, vcc, 0, v7, vcc
	v_add_co_u32_e32 v6, vcc, s18, v6
	global_load_dword v240, v[14:15], off offset:-2048
	global_load_dword v25, v[14:15], off offset:-4096
	global_load_dword v241, v[14:15], off offset:2048
	global_load_dword v24, v[14:15], off
	v_addc_co_u32_e32 v7, vcc, 0, v7, vcc
	global_load_dword v242, v[6:7], off offset:-2048
	global_load_dword v23, v[6:7], off offset:-4096
	global_load_dword v243, v[6:7], off offset:2048
	global_load_dword v22, v[6:7], off
	v_lshl_add_u64 v[6:7], v[2:3], 3, s[36:37]
	v_add_u32_e32 v246, 0x200, v2
	v_mov_b32_e32 v247, v3
	v_lshl_add_u64 v[246:247], v[246:247], 3, s[36:37]
	global_load_dwordx2 v[244:245], v[246:247], off
	global_load_dwordx2 v[6:7], v[6:7], off
	s_branch .Lcs2_aj
.Lcs2_a2:
	v_cndmask_b32_e64 v2, 0, 1, s[54:55]
	v_cmp_ne_u32_e64 s[4:5], 1, v2
	v_add_u32_e32 v2, s3, v172
	v_ashrrev_i32_e32 v3, 31, v2
	v_lshlrev_b64 v[6:7], 2, v[2:3]
	v_lshl_add_u64 v[14:15], s[42:43], 0, v[6:7]
	v_add_co_u32_e32 v8, vcc, 0x1000, v14
	v_lshl_add_u64 v[6:7], s[50:51], 0, v[6:7]
	s_nop 0
	v_addc_co_u32_e32 v9, vcc, 0, v15, vcc
	v_add_co_u32_e32 v8, vcc, 0x1000, v6
	s_mov_b32 s26, s61
	s_nop 0
	v_addc_co_u32_e32 v9, vcc, 0, v7, vcc
	v_add_co_u32_e32 v8, vcc, s48, v14
	s_mov_b32 s27, s60
	s_nop 0
	v_addc_co_u32_e32 v9, vcc, 0, v15, vcc
	v_add_co_u32_e32 v8, vcc, s48, v6
	s_mov_b32 s79, s61
	s_nop 0
	v_addc_co_u32_e32 v9, vcc, 0, v7, vcc
	v_add_co_u32_e32 v8, vcc, 0x3000, v14
	s_mov_b32 s30, s80
	s_nop 0
	v_addc_co_u32_e32 v9, vcc, 0, v15, vcc
	v_add_co_u32_e32 v8, vcc, 0x3000, v6
	s_mov_b32 s31, s60
	s_nop 0
	v_addc_co_u32_e32 v9, vcc, 0, v7, vcc
	v_add_co_u32_e32 v12, vcc, s40, v14
	s_nop 0
	v_addc_co_u32_e32 v13, vcc, 0, v15, vcc
	v_add_co_u32_e32 v16, vcc, s40, v6
	s_nop 0
	v_addc_co_u32_e32 v17, vcc, 0, v7, vcc
	v_add_co_u32_e32 v14, vcc, s33, v14
	s_nop 0
	s_nop 0
	v_addc_co_u32_e32 v15, vcc, 0, v15, vcc
	v_add_co_u32_e32 v22, vcc, s33, v6
	s_nop 0
	v_addc_co_u32_e32 v23, vcc, 0, v7, vcc
	v_add_co_u32_e32 v14, vcc, s1, v6
	s_mov_b32 s28, s80
	s_nop 0
	v_addc_co_u32_e32 v15, vcc, 0, v7, vcc
	v_add_co_u32_e32 v14, vcc, s92, v6
	s_mov_b32 s29, s61
	s_nop 0
	v_addc_co_u32_e32 v15, vcc, 0, v7, vcc
	v_add_co_u32_e32 v14, vcc, s0, v6
	s_mov_b32 s44, s61
	s_nop 0
	v_addc_co_u32_e32 v15, vcc, 0, v7, vcc
	v_add_co_u32_e32 v6, vcc, s18, v6
	v_addc_co_u32_e32 v7, vcc, 0, v7, vcc
	v_lshl_add_u64 v[6:7], v[2:3], 3, s[36:37]
	s_waitcnt vmcnt(0)
	v_mov_b32_e32 v4, v200
	v_mov_b32_e32 v29, v201
	v_mov_b32_e32 v10, v202
	v_mov_b32_e32 v32, v203
	v_mov_b32_e32 v30, v204
	v_mov_b32_e32 v35, v205
	v_mov_b32_e32 v31, v206
	v_mov_b32_e32 v34, v207
	v_mov_b32_e32 v8, v208
	v_mov_b32_e32 v19, v209
	v_mov_b32_e32 v13, v210
	v_mov_b32_e32 v18, v211
	v_mov_b32_e32 v16, v212
	v_mov_b32_e32 v21, v213
	v_mov_b32_e32 v17, v214
	v_mov_b32_e32 v20, v215
	v_mov_b32_e32 v33, v236
	v_mov_b32_e32 v28, v237
	v_mov_b32_e32 v45, v238
	v_mov_b32_e32 v44, v239
	v_mov_b32_e32 v25, v240
	v_mov_b32_e32 v24, v241
	v_mov_b32_e32 v23, v242
	v_mov_b32_e32 v22, v243
	v_mov_b32_e32 v6, v244
	v_mov_b32_e32 v7, v245
; #define FFT_HD __device__ __attribute__((always_inline))
; template <int R> FFT_HD inline void reg_fwd(cf2 (&v)[1 << R], cf2 th) { dft_fwd_reg<R>(v); tw_apply<R, 1, false>(v, th, th); }
; template <int R> FFT_HD inline void dft_fwd_reg(cf2 (&v)[1 << R]) {
;     constexpr int n = 1 << R;
; #pragma unroll
;     for (int s = 0; s < R; ++s) {
;         const int half = n >> (s + 1);
; #pragma unroll
;         for (int m = 0; m < n; ++m) {
;             if ((m & half) == 0) {
;                 const int ml = m & (half - 1), tk = ml * (16 / half);
;                 const cf2 a = v[m], b = v[m + half];
;                 v[m].x = a.x + b.x; v[m].y = a.y + b.y;
;                 const cf2 d = {a.x - b.x, a.y - b.y};
;                 if (tk == 0) v[m + half] = d;
;                 else if (tk == 8) { v[m + half].x = d.y; v[m + half].y = -d.x; }
;                 else { const cf2 w = {fc32(tk), -fs32(tk)}; v[m + half] = cmulf(d, w); }
;             }
;         }
;     }
; }
; __device__ __forceinline__ void hyena_conv_s2(const float* HYT, float* ZOUT, const float* FILT, const cf2* TW, LAS unsigned char* lds, int vb, int nb, int tid_in) {
;     ...
;             for (int m = 0; m < 16; ++m) { v[m].x = m < 8 ? hv[grp + 1024 * m] : 0.f; v[m].y = f0[grp + 1024 * m]; }
;             reg_fwd<4>(v, TW[grp]); grp_store<4, 1024>(X, grp, v); }
.Lcs2_aj:
	s_mov_b32 s45, s80
	s_mov_b32 s83, s84
	s_mov_b32 s81, s82
	s_waitcnt vmcnt(23)
	v_mov_b32_e32 v69, v29
	s_waitcnt vmcnt(22)
	v_mov_b32_e32 v5, v10
	v_pk_add_f32 v[40:41], v[4:5], 0 op_sel_hi:[1,0]
	v_mul_f32_e32 v70, 0x3ec3ef15, v10
	v_lshrrev_b32_e32 v3, 22, v3
	v_add_lshl_u32 v3, v2, v3, 4
	v_and_b32_e32 v3, 0xffffc000, v3
	v_and_b32_e32 v2, 0x3ff, v2
	s_movk_i32 s3, 0x200
	s_mov_b64 s[54:55], 0
	s_and_b64 vcc, exec, s[4:5]
	s_waitcnt vmcnt(18)
	v_pk_add_f32 v[54:55], v[30:31], 0 op_sel_hi:[1,0]
	s_waitcnt vmcnt(15)
	v_mov_b32_e32 v66, v19
	s_waitcnt vmcnt(14)
	v_mov_b32_e32 v9, v13
	v_mul_f32_e32 v14, 0x3f6c835e, v13
	v_pk_add_f32 v[74:75], v[8:9], 0 op_sel_hi:[1,0]
	v_mul_f32_e32 v65, 0x3ec3ef15, v13
	v_sub_f32_e32 v5, v41, v75
	v_mul_f32_e32 v5, 0x3f3504f3, v5
	s_waitcnt vmcnt(10)
	v_pk_add_f32 v[84:85], v[16:17], 0 op_sel_hi:[1,0]
	s_nop 0
	v_pk_add_f32 v[82:83], v[54:55], v[84:85]
	s_waitcnt vmcnt(8)
	v_mov_b32_e32 v71, v33
	s_waitcnt vmcnt(7)
	v_sub_f32_e32 v11, v32, v28
	v_mul_f32_e32 v12, 0x3ec3ef15, v11
	v_pk_fma_f32 v[26:27], v[10:11], s[26:27], v[12:13] op_sel_hi:[1,1,0]
	v_pk_add_f32 v[46:47], v[28:29], v[32:33]
	v_sub_f32_e32 v10, v55, v85
	v_mul_f32_e32 v68, 0x3f6c835e, v11
	s_waitcnt vmcnt(5)
	v_pk_add_f32 v[72:73], v[34:35], v[44:45]
	v_mov_b32_e32 v32, v35
	v_mov_b32_e32 v33, v34
	v_mov_b32_e32 v34, v45
	v_mov_b32_e32 v35, v44
	v_pk_add_f32 v[32:33], v[32:33], v[34:35] neg_lo:[0,1] neg_hi:[0,1]
	v_mov_b32_e32 v34, v31
	v_mov_b32_e32 v35, v30
	s_waitcnt vmcnt(3)
	v_sub_f32_e32 v12, v18, v24
	v_pk_add_f32 v[78:79], v[18:19], v[24:25]
	v_mul_f32_e32 v67, 0x3f6c835e, v12
	s_waitcnt vmcnt(1)
	v_pk_add_f32 v[86:87], v[20:21], v[22:23]
	v_pk_fma_f32 v[36:37], v[12:13], s[78:79], v[14:15] op_sel_hi:[1,1,0] neg_lo:[0,0,1] neg_hi:[0,0,1]
	s_waitcnt vmcnt(0)
	v_pk_mul_f32 v[38:39], v[6:7], v[6:7] op_sel:[1,1] op_sel_hi:[0,1]
	v_pk_fma_f32 v[42:43], v[6:7], v[6:7], v[38:39] op_sel_hi:[0,1,1] neg_lo:[0,0,1] neg_hi:[0,0,1]
	v_pk_fma_f32 v[50:51], v[6:7], v[6:7], v[38:39] op_sel_hi:[0,1,1]
	v_pk_mov_b32 v[38:39], v[50:51], v[42:43] op_sel:[1,0]
	v_pk_add_f32 v[12:13], v[40:41], v[74:75]
	v_pk_add_f32 v[14:15], v[46:47], v[78:79]
	v_pk_add_f32 v[88:89], v[72:73], v[86:87]
	v_mov_b32_e32 v52, v42
	v_mov_b32_e32 v53, v51
	v_pk_mul_f32 v[58:59], v[50:51], v[38:39] op_sel:[1,0]
	v_mul_f32_e32 v18, 0x3f3504f3, v10
	v_pk_add_f32 v[10:11], v[12:13], v[82:83] neg_lo:[0,1] neg_hi:[0,1]
	v_pk_add_f32 v[90:91], v[14:15], v[88:89] neg_lo:[0,1] neg_hi:[0,1]
	v_pk_fma_f32 v[56:57], v[42:43], v[52:53], v[58:59] op_sel_hi:[0,1,1] neg_lo:[0,0,1] neg_hi:[0,0,1]
	v_pk_fma_f32 v[58:59], v[42:43], v[52:53], v[58:59] op_sel_hi:[0,1,1]
	v_pk_add_f32 v[80:81], v[10:11], v[90:91]
	v_pk_add_f32 v[48:49], v[10:11], v[90:91] neg_lo:[0,1] neg_hi:[0,1]
	v_sub_f32_e32 v10, v91, v11
	v_pk_mov_b32 v[90:91], v[58:59], v[56:57] op_sel:[1,0]
	v_mov_b32_e32 v92, v56
	v_mov_b32_e32 v93, v59
	v_pk_mul_f32 v[90:91], v[10:11], v[90:91] op_sel_hi:[0,1]
	v_pk_mul_f32 v[60:61], v[56:57], v[92:93] op_sel_hi:[0,1]
	v_pk_fma_f32 v[10:11], v[80:81], v[56:57], v[90:91] neg_lo:[0,0,1] neg_hi:[0,0,1]
	v_pk_fma_f32 v[90:91], v[80:81], v[92:93], v[90:91] op_sel_hi:[0,1,1]
	v_pk_fma_f32 v[94:95], v[92:93], v[58:59], v[60:61] op_sel:[0,1,1] op_sel_hi:[1,1,0] neg_lo:[1,0,0] neg_hi:[1,0,0]
	v_pk_fma_f32 v[96:97], v[92:93], v[58:59], v[60:61] op_sel:[0,1,1] op_sel_hi:[1,1,0]
	v_mov_b32_e32 v11, v91
	v_mov_b32_e32 v90, v12
	v_mov_b32_e32 v91, v15
	v_mov_b32_e32 v92, v82
	v_mov_b32_e32 v93, v89
	v_pk_mov_b32 v[12:13], v[12:13], v[14:15] op_sel:[1,0]
	v_pk_mov_b32 v[14:15], v[82:83], v[88:89] op_sel:[1,0]
	v_pk_add_f32 v[90:91], v[90:91], v[92:93]
	v_pk_add_f32 v[14:15], v[12:13], v[14:15]
	s_mov_b32 s26, s60
	s_mov_b32 s27, s80
	v_pk_add_f32 v[82:83], v[90:91], v[14:15] neg_lo:[0,1] neg_hi:[0,1]
	v_pk_mul_f32 v[30:31], v[34:35], s[26:27]
	v_pk_mul_f32 v[44:45], v[32:33], s[30:31]
	v_sub_f32_e32 v9, v46, v78
	v_pk_mul_f32 v[88:89], v[82:83], v[96:97] op_sel:[1,0] op_sel_hi:[0,0]
	v_pk_fma_f32 v[30:31], v[32:33], s[28:29], v[30:31] op_sel:[0,0,1] op_sel_hi:[1,1,0]
	v_pk_fma_f32 v[32:33], v[34:35], s[44:45], v[44:45] op_sel:[0,0,1] op_sel_hi:[1,1,0] neg_lo:[1,0,0] neg_hi:[1,0,0]
	v_mov_b32_e32 v34, v21
	v_mov_b32_e32 v35, v20
	v_mov_b32_e32 v20, v23
	v_mov_b32_e32 v21, v22
	v_mov_b32_e32 v22, v17
	v_mov_b32_e32 v23, v16
	v_mul_f32_e32 v24, 0x3f3504f3, v9
	v_pk_add_f32 v[12:13], v[90:91], v[14:15]
	v_pk_fma_f32 v[14:15], v[82:83], v[94:95], v[88:89] op_sel:[0,1,0] neg_lo:[0,0,1] neg_hi:[0,0,1]
	v_pk_fma_f32 v[82:83], v[82:83], v[94:95], v[88:89] op_sel:[0,1,0]
	v_mov_b32_e32 v41, v47
	v_mov_b32_e32 v75, v79
	v_pk_add_f32 v[20:21], v[34:35], v[20:21] neg_lo:[0,1] neg_hi:[0,1]
	v_pk_mul_f32 v[16:17], v[22:23], s[44:45]
	v_pk_add_f32 v[46:47], v[40:41], v[74:75] neg_lo:[0,1] neg_hi:[0,1]
	v_add_f32_e32 v82, v24, v5
	v_pk_mov_b32 v[40:41], v[72:73], v[54:55] op_sel:[1,0]
	v_pk_mov_b32 v[54:55], v[86:87], v[84:85] op_sel:[1,0]
	v_sub_f32_e32 v24, v72, v86
	v_pk_add_f32 v[28:29], v[68:69], v[70:71] neg_lo:[0,1] neg_hi:[0,1]
	v_mov_b32_e32 v64, v25
	v_pk_fma_f32 v[16:17], v[20:21], s[30:31], v[16:17] op_sel:[0,0,1] op_sel_hi:[1,1,0] neg_lo:[0,0,1] neg_hi:[0,0,1]
	v_pk_mul_f32 v[20:21], v[20:21], s[82:83]
	v_mov_b32_e32 v37, v8
	v_mov_b32_e32 v15, v83
	v_fma_f32 v83, v9, s80, -v5
	v_pk_add_f32 v[54:55], v[40:41], v[54:55] neg_lo:[0,1] neg_hi:[0,1]
	v_pk_fma_f32 v[84:85], v[24:25], s[80:81], v[18:19] op_sel_hi:[0,1,0] neg_lo:[0,0,1] neg_hi:[0,0,1]
	v_pk_add_f32 v[24:25], v[66:67], v[64:65] neg_lo:[0,1] neg_hi:[0,1]
	v_pk_fma_f32 v[20:21], v[22:23], s[26:27], v[20:21] op_sel:[0,0,1] op_sel_hi:[1,1,0] neg_lo:[1,0,0] neg_hi:[1,0,0]
; #define FFT_HD __device__ __attribute__((always_inline))
; template <int R> FFT_HD inline void dft_fwd_reg(cf2 (&v)[1 << R]) {
;     constexpr int n = 1 << R;
; #pragma unroll
;     for (int s = 0; s < R; ++s) {
;         const int half = n >> (s + 1);
; #pragma unroll
;         for (int m = 0; m < n; ++m) {
;             if ((m & half) == 0) {
;                 const int ml = m & (half - 1), tk = ml * (16 / half);
;                 const cf2 a = v[m], b = v[m + half];
;                 v[m].x = a.x + b.x; v[m].y = a.y + b.y;
;                 const cf2 d = {a.x - b.x, a.y - b.y};
;                 if (tk == 0) v[m + half] = d;
;                 else if (tk == 8) { v[m + half].x = d.y; v[m + half].y = -d.x; }
;                 else { const cf2 w = {fc32(tk), -fs32(tk)}; v[m + half] = cmulf(d, w); }
;             }
;         }
;     }
; }
; template <int R, int F, bool CONJ> FFT_HD inline void tw_apply(cf2 (&v)[1 << R], cf2 pf, cf2 th) {
;     constexpr int j = fbrev(F, R);
;     v[j] = CONJ ? cmulcf(v[j], pf) : cmulf(v[j], pf);
;     if constexpr (2 * F < (1 << R)) {
;         const cf2 p2 = cmulf(pf, pf);
;         tw_apply<R, 2 * F, CONJ>(v, p2, th);
;         const cf2 p3 = cmulf(p2, th);
;         tw_apply<R, 2 * F + 1, CONJ>(v, p3, th);
;     }
; }
	v_mov_b32_e32 v5, v26
	v_pk_add_f32 v[66:67], v[28:29], v[36:37]
	v_pk_add_f32 v[68:69], v[28:29], v[36:37] neg_lo:[0,1] neg_hi:[0,1]
	v_pk_add_f32 v[40:41], v[46:47], v[54:55]
	v_pk_add_f32 v[72:73], v[46:47], v[54:55] neg_lo:[0,1] neg_hi:[0,1]
	v_pk_add_f32 v[22:23], v[4:5], v[24:25]
	v_mov_b32_e32 v68, v66
	v_pk_add_f32 v[34:35], v[30:31], v[16:17] neg_lo:[0,1] neg_hi:[0,1]
	v_pk_add_f32 v[44:45], v[32:33], v[20:21] neg_lo:[0,1] neg_hi:[0,1]
	v_pk_add_f32 v[16:17], v[30:31], v[16:17]
	v_pk_add_f32 v[20:21], v[32:33], v[20:21]
	v_mov_b32_e32 v72, v40
	v_pk_add_f32 v[74:75], v[82:83], v[84:85]
	v_mov_b32_e32 v47, v83
	v_mov_b32_e32 v55, v85
	v_pk_add_f32 v[32:33], v[22:23], v[16:17] neg_lo:[0,1] neg_hi:[0,1]
	v_pk_add_f32 v[70:71], v[68:69], v[20:21] neg_lo:[0,1] neg_hi:[0,1]
	v_mov_b32_e32 v68, v22
	v_mov_b32_e32 v30, v16
	v_mov_b32_e32 v31, v21
	v_pk_mov_b32 v[22:23], v[22:23], v[66:67] op_sel:[1,0]
	v_pk_mov_b32 v[16:17], v[16:17], v[20:21] op_sel:[1,0]
	v_pk_add_f32 v[46:47], v[46:47], v[54:55] neg_lo:[0,1] neg_hi:[0,1]
	v_pk_add_f32 v[54:55], v[72:73], v[74:75]
	v_pk_add_f32 v[30:31], v[68:69], v[30:31]
	v_pk_add_f32 v[16:17], v[22:23], v[16:17]
	v_pk_add_f32 v[78:79], v[72:73], v[74:75] neg_lo:[0,1] neg_hi:[0,1]
	v_pk_mul_f32 v[72:73], v[38:39], v[54:55] op_sel:[0,1]
	v_pk_add_f32 v[20:21], v[30:31], v[16:17]
	v_mov_b32_e32 v62, v96
	v_mov_b32_e32 v63, v95
	v_pk_fma_f32 v[38:39], v[42:43], v[54:55], v[72:73] neg_lo:[0,0,1] neg_hi:[0,0,1]
	v_pk_fma_f32 v[52:53], v[52:53], v[54:55], v[72:73] op_sel_hi:[1,0,1]
	v_pk_add_f32 v[22:23], v[30:31], v[16:17] neg_lo:[0,1] neg_hi:[0,1]
	v_pk_mul_f32 v[30:31], v[6:7], v[20:21] op_sel:[1,1] op_sel_hi:[0,1]
	v_pk_mov_b32 v[60:61], v[94:95], v[96:97] op_sel:[1,0]
	v_pk_mul_f32 v[62:63], v[6:7], v[62:63]
	v_mov_b32_e32 v39, v53
	v_pk_mul_f32 v[52:53], v[6:7], v[50:51] op_sel:[1,1] op_sel_hi:[0,1]
	v_pk_fma_f32 v[16:17], v[6:7], v[20:21], v[30:31] neg_lo:[0,0,1] neg_hi:[0,0,1]
	v_pk_fma_f32 v[20:21], v[6:7], v[20:21], v[30:31] op_sel_hi:[1,0,1]
	v_pk_mul_f32 v[60:61], v[6:7], v[60:61]
	v_pk_fma_f32 v[50:51], v[6:7], v[42:43], v[52:53] op_sel_hi:[1,0,1] neg_lo:[0,0,1] neg_hi:[0,0,1]
	v_pk_fma_f32 v[42:43], v[6:7], v[42:43], v[52:53] op_sel_hi:[1,0,1]
	v_mov_b32_e32 v17, v21
	v_pk_add_f32 v[20:21], v[62:63], v[62:63] op_sel:[1,0] op_sel_hi:[1,0]
	v_pk_mov_b32 v[54:55], v[42:43], v[50:51] op_sel:[1,0]
	v_pk_mul_f32 v[30:31], v[22:23], v[20:21] op_sel:[1,0] op_sel_hi:[0,1]
	v_pk_add_f32 v[60:61], v[60:61], v[60:61] op_sel:[0,1] op_sel_hi:[0,1] neg_lo:[0,1] neg_hi:[0,1]
	v_mov_b32_e32 v52, v50
	v_mov_b32_e32 v53, v43
	v_pk_mul_f32 v[42:43], v[42:43], v[54:55] op_sel:[1,0]
	v_pk_fma_f32 v[20:21], v[22:23], v[60:61], v[30:31] neg_lo:[0,0,1] neg_hi:[0,0,1]
	v_pk_fma_f32 v[22:23], v[22:23], v[60:61], v[30:31]
	v_pk_fma_f32 v[86:87], v[50:51], v[52:53], v[42:43] op_sel_hi:[0,1,1] neg_lo:[0,0,1] neg_hi:[0,0,1]
	v_pk_fma_f32 v[72:73], v[50:51], v[52:53], v[42:43] op_sel_hi:[0,1,1]
	v_sub_f32_e32 v18, v82, v84
	v_mov_b32_e32 v21, v23
	v_pk_mul_f32 v[22:23], v[6:7], v[58:59] op_sel:[1,1] op_sel_hi:[0,1]
	v_pk_add_f32 v[42:43], v[40:41], v[18:19] op_sel:[1,0] op_sel_hi:[1,0] neg_lo:[0,1] neg_hi:[0,1]
	v_pk_mov_b32 v[82:83], v[72:73], v[86:87] op_sel:[1,0]
	v_pk_fma_f32 v[60:61], v[6:7], v[56:57], v[22:23] op_sel_hi:[1,0,1] neg_lo:[0,0,1] neg_hi:[0,0,1]
	v_pk_fma_f32 v[22:23], v[6:7], v[56:57], v[22:23] op_sel_hi:[1,0,1]
	v_mov_b32_e32 v74, v86
	v_mov_b32_e32 v75, v73
	v_pk_add_f32 v[88:89], v[46:47], v[46:47] op_sel:[0,1] op_sel_hi:[0,1]
	v_pk_mul_f32 v[84:85], v[42:43], v[82:83]
	v_mov_b32_e32 v62, v60
	v_mov_b32_e32 v63, v23
	v_pk_fma_f32 v[42:43], v[88:89], v[86:87], v[84:85] neg_lo:[0,0,1] neg_hi:[0,0,1]
	v_pk_fma_f32 v[84:85], v[88:89], v[74:75], v[84:85]
	v_pk_mov_b32 v[66:67], v[22:23], v[60:61] op_sel:[1,0]
	v_pk_mul_f32 v[22:23], v[62:63], v[22:23] op_sel:[0,1]
	v_mov_b32_e32 v43, v85
	v_pk_mul_f32 v[84:85], v[74:75], v[72:73] op_sel:[0,1]
	v_pk_fma_f32 v[68:69], v[60:61], v[66:67], v[22:23] op_sel_hi:[0,1,1] neg_lo:[0,0,1] neg_hi:[0,0,1]
	v_pk_fma_f32 v[22:23], v[60:61], v[66:67], v[22:23] op_sel_hi:[0,1,1]
	v_mov_b32_e32 v77, v81
	v_pk_mov_b32 v[80:81], v[80:81], v[48:49] op_sel:[1,0]
	v_pk_fma_f32 v[88:89], v[86:87], v[82:83], v[84:85] op_sel_hi:[0,1,1] neg_lo:[0,0,1] neg_hi:[0,0,1]
	v_pk_fma_f32 v[82:83], v[86:87], v[82:83], v[84:85] op_sel_hi:[0,1,1]
	v_mov_b32_e32 v30, v22
	v_mov_b32_e32 v31, v69
	v_pk_mov_b32 v[56:57], v[68:69], v[22:23] op_sel:[1,0]
	v_pk_mul_f32 v[22:23], v[78:79], v[22:23] op_sel:[1,0] op_sel_hi:[0,0]
	v_mov_b32_e32 v76, v48
	v_pk_mul_f32 v[80:81], v[80:81], v[82:83] op_sel_hi:[1,0]
	v_pk_mul_f32 v[58:59], v[6:7], v[30:31]
	v_pk_fma_f32 v[30:31], v[78:79], v[68:69], v[22:23] op_sel:[0,1,0] neg_lo:[0,0,1] neg_hi:[0,0,1]
	v_pk_fma_f32 v[22:23], v[78:79], v[68:69], v[22:23] op_sel:[0,1,0]
	v_mov_b32_e32 v84, v82
	v_mov_b32_e32 v85, v89
	v_pk_mov_b32 v[82:83], v[88:89], v[82:83] op_sel:[1,0]
	v_pk_fma_f32 v[48:49], v[48:49], v[88:89], v[80:81] op_sel:[0,1,0] neg_lo:[0,0,1] neg_hi:[0,0,1]
	v_pk_fma_f32 v[76:77], v[76:77], v[88:89], v[80:81] op_sel:[0,1,0]
	v_sub_f32_e32 v22, v71, v33
	v_mov_b32_e32 v49, v77
	v_pk_mul_f32 v[76:77], v[6:7], v[82:83]
	v_pk_mul_f32 v[80:81], v[6:7], v[84:85]
	v_pk_add_f32 v[82:83], v[32:33], v[70:71]
	v_pk_add_f32 v[84:85], v[32:33], v[70:71] neg_lo:[0,1] neg_hi:[0,1]
	v_pk_mul_f32 v[32:33], v[22:23], v[66:67] op_sel_hi:[0,1]
	v_mov_b32_e32 v31, v23
	v_pk_fma_f32 v[22:23], v[82:83], v[60:61], v[32:33] neg_lo:[0,0,1] neg_hi:[0,0,1]
	v_pk_fma_f32 v[32:33], v[82:83], v[62:63], v[32:33] op_sel_hi:[0,1,1]
	v_mov_b32_e32 v23, v33
; #define FFT_HD __device__ __attribute__((always_inline))
; template <int R> FFT_HD inline void reg_fwd(cf2 (&v)[1 << R], cf2 th) { dft_fwd_reg<R>(v); tw_apply<R, 1, false>(v, th, th); }
; template <int R, int F, bool CONJ> FFT_HD inline void tw_apply(cf2 (&v)[1 << R], cf2 pf, cf2 th) {
;     constexpr int j = fbrev(F, R);
;     v[j] = CONJ ? cmulcf(v[j], pf) : cmulf(v[j], pf);
;     if constexpr (2 * F < (1 << R)) {
;         const cf2 p2 = cmulf(pf, pf);
;         tw_apply<R, 2 * F, CONJ>(v, p2, th);
;         const cf2 p3 = cmulf(p2, th);
;         tw_apply<R, 2 * F + 1, CONJ>(v, p3, th);
;     }
; }
; __device__ __forceinline__ void hyena_conv_s2(const float* HYT, float* ZOUT, const float* FILT, const cf2* TW, LAS unsigned char* lds, int vb, int nb, int tid_in) {
;     ...
; #pragma unroll 1
;         for (int q = 0; q < 2; ++q) { const int grp = tid + 512 * q; cf2 v[16];
; #pragma unroll
;             for (int m = 0; m < 16; ++m) { v[m].x = m < 8 ? hv[grp + 1024 * m] : 0.f; v[m].y = f0[grp + 1024 * m]; }
;             reg_fwd<4>(v, TW[grp]); grp_store<4, 1024>(X, grp, v); }
	v_pk_mov_b32 v[32:33], v[82:83], v[84:85] op_sel:[1,0]
	v_pk_add_f32 v[60:61], v[80:81], v[80:81] op_sel:[1,0] op_sel_hi:[1,0]
	v_mov_b32_e32 v86, v84
	v_mov_b32_e32 v87, v83
	v_pk_mul_f32 v[60:61], v[32:33], v[60:61]
	v_pk_add_f32 v[62:63], v[76:77], v[76:77] op_sel:[0,1] op_sel_hi:[0,1] neg_lo:[0,1] neg_hi:[0,1]
	v_pk_fma_f32 v[32:33], v[84:85], v[62:63], v[60:61] neg_lo:[0,0,1] neg_hi:[0,0,1]
	v_pk_fma_f32 v[60:61], v[86:87], v[62:63], v[60:61]
	v_pk_mul_f32 v[66:67], v[6:7], v[74:75]
	v_mul_f32_e32 v60, v6, v73
	v_mov_b32_e32 v68, v28
	v_mov_b32_e32 v69, v66
	v_mov_b32_e32 v37, v67
	v_mov_b32_e32 v33, v61
	v_pk_fma_f32 v[60:61], v[6:7], v[74:75], v[60:61] op_sel:[1,0,0] op_sel_hi:[0,1,0]
	v_pk_add_f32 v[36:37], v[68:69], v[36:37] neg_lo:[0,1] neg_hi:[0,1]
	v_mov_b32_e32 v27, v66
	v_mov_b32_e32 v66, v25
	v_pk_mul_f32 v[62:63], v[60:61], v[60:61]
	v_pk_add_f32 v[26:27], v[26:27], v[66:67] neg_lo:[0,1] neg_hi:[0,1]
	v_mov_b32_e32 v66, v187
	v_mov_b32_e32 v67, v60
	v_pk_mul_f32 v[70:71], v[36:37], v[36:37]
	v_pk_mul_f32 v[68:69], v[36:37], s[80:81]
	v_pk_mul_f32 v[26:27], v[26:27], v[66:67]
	v_mov_b32_e32 v5, v71
	v_mov_b32_e32 v25, v62
	v_pk_add_f32 v[4:5], v[4:5], v[24:25] neg_lo:[0,1] neg_hi:[0,1]
	v_pk_fma_f32 v[24:25], v[36:37], v[66:67], v[26:27] neg_lo:[0,0,1] neg_hi:[0,0,1]
	v_pk_fma_f32 v[62:63], v[36:37], v[66:67], v[26:27]
	v_mov_b32_e32 v9, v26
	v_pk_mov_b32 v[26:27], v[28:29], v[68:69] op_sel:[1,0]
	v_mul_f32_e32 v64, 0x3f3504f3, v35
	v_pk_add_f32 v[8:9], v[8:9], v[26:27]
	v_pk_fma_f32 v[64:65], v[44:45], s[80:81], v[64:65] op_sel_hi:[0,1,0] neg_lo:[0,0,1] neg_hi:[0,0,1]
	v_pk_mov_b32 v[26:27], v[44:45], v[8:9] op_sel:[1,0]
	v_pk_mul_f32 v[56:57], v[6:7], v[56:57]
	v_pk_add_f32 v[28:29], v[26:27], v[4:5]
	v_pk_add_f32 v[26:27], v[26:27], v[34:35] op_sel_hi:[1,0] neg_lo:[0,1] neg_hi:[0,1]
	v_pk_add_f32 v[58:59], v[58:59], v[58:59] op_sel:[1,0] op_sel_hi:[1,0]
	v_mov_b32_e32 v29, v27
	v_pk_mov_b32 v[26:27], v[8:9], v[24:25] op_sel:[1,0]
	v_pk_add_f32 v[56:57], v[56:57], v[56:57] op_sel:[0,1] op_sel_hi:[0,1] neg_lo:[0,1] neg_hi:[0,1]
	v_pk_add_f32 v[26:27], v[26:27], v[64:65]
	v_mov_b32_e32 v35, v64
	v_pk_add_f32 v[68:69], v[28:29], v[26:27]
	v_pk_add_f32 v[26:27], v[28:29], v[26:27] neg_lo:[0,1] neg_hi:[0,1]
	v_pk_add_f32 v[24:25], v[24:25], v[64:65] op_sel:[0,1] op_sel_hi:[1,0] neg_lo:[0,1] neg_hi:[0,1]
	v_pk_mul_f32 v[58:59], v[26:27], v[58:59] op_sel:[1,0] op_sel_hi:[0,1]
	v_pk_fma_f32 v[64:65], v[26:27], v[56:57], v[58:59] neg_lo:[0,0,1] neg_hi:[0,0,1]
	v_pk_fma_f32 v[26:27], v[26:27], v[56:57], v[58:59]
	v_pk_mov_b32 v[66:67], v[44:45], v[6:7] op_sel:[1,0]
	v_pk_add_f32 v[44:45], v[8:9], v[34:35]
	v_pk_add_f32 v[8:9], v[8:9], v[34:35] neg_lo:[0,1] neg_hi:[0,1]
	v_mov_b32_e32 v65, v27
	v_pk_mul_f32 v[26:27], v[54:55], v[68:69] op_sel:[0,1]
	v_mov_b32_e32 v34, v44
	v_mov_b32_e32 v35, v9
	v_pk_fma_f32 v[50:51], v[50:51], v[68:69], v[26:27] neg_lo:[0,0,1] neg_hi:[0,0,1]
	v_pk_fma_f32 v[26:27], v[52:53], v[68:69], v[26:27] op_sel_hi:[1,0,1]
	v_pk_add_f32 v[70:71], v[4:5], v[66:67] neg_lo:[0,1] neg_hi:[0,1]
	v_pk_mul_f32 v[28:29], v[62:63], v[6:7]
	v_pk_add_f32 v[34:35], v[34:35], v[8:9] op_sel:[0,1] op_sel_hi:[1,0]
	v_mov_b32_e32 v51, v27
	v_pk_mov_b32 v[26:27], v[36:37], v[60:61] op_sel:[1,0]
	v_pk_add_f32 v[8:9], v[44:45], v[8:9] op_sel:[0,1] op_sel_hi:[0,1] neg_lo:[0,1] neg_hi:[0,1]
	v_mov_b32_e32 v61, v37
	v_mov_b32_e32 v28, v24
	v_pk_add_f32 v[24:25], v[70:71], v[24:25]
	v_pk_mul_f32 v[8:9], v[8:9], v[60:61]
	v_pk_mul_f32 v[66:67], v[4:5], v[66:67]
	v_pk_fma_f32 v[36:37], v[24:25], v[26:27], v[8:9] neg_lo:[0,0,1] neg_hi:[0,0,1]
	v_pk_fma_f32 v[8:9], v[24:25], v[26:27], v[8:9] op_sel_hi:[0,1,1]
	v_pk_add_f32 v[18:19], v[40:41], v[18:19] op_sel:[1,0] op_sel_hi:[1,0]
	v_mov_b32_e32 v4, v63
	v_mov_b32_e32 v37, v9
	v_pk_add_f32 v[8:9], v[46:47], v[46:47] op_sel:[0,1] op_sel_hi:[0,1] neg_lo:[0,1] neg_hi:[0,1]
	v_mov_b32_e32 v62, v5
	v_pk_mul_f32 v[18:19], v[18:19], v[4:5]
	v_mov_b32_e32 v66, v70
	v_pk_fma_f32 v[24:25], v[8:9], v[62:63], v[18:19] neg_lo:[0,0,1] neg_hi:[0,0,1]
	v_pk_fma_f32 v[8:9], v[8:9], v[62:63], v[18:19]
	v_pk_mul_f32 v[4:5], v[6:7], v[4:5]
	v_mov_b32_e32 v25, v9
	v_pk_add_f32 v[8:9], v[66:67], v[28:29] neg_lo:[0,1] neg_hi:[0,1]
	v_mov_b32_e32 v6, v34
	v_mov_b32_e32 v7, v8
	v_pk_add_f32 v[4:5], v[4:5], v[4:5] op_sel:[1,0] op_sel_hi:[1,0]
	s_nop 0
	v_pk_mul_f32 v[4:5], v[6:7], v[4:5]
	v_pk_mov_b32 v[6:7], v[8:9], v[34:35] op_sel:[1,0]
	s_nop 0
	v_pk_fma_f32 v[18:19], v[8:9], v[6:7], v[4:5] neg_lo:[0,0,1] neg_hi:[0,0,1]
	v_pk_fma_f32 v[4:5], v[8:9], v[6:7], v[4:5]
	s_nop 0
	v_or_b32_e32 v4, v3, v2
	v_bitop3_b32 v2, v3, s19, v2 bitop3:0xc8
	v_lshlrev_b32_e32 v3, 3, v4
	v_add3_u32 v2, 0, v2, v3
	v_add_u32_e32 v3, 0x12000, v2
	ds_write2st64_b64 v2, v[12:13], v[14:15] offset1:18
	ds_write2st64_b64 v2, v[10:11], v[48:49] offset0:36 offset1:54
	ds_write2st64_b64 v2, v[38:39], v[30:31] offset0:72 offset1:90
	ds_write2st64_b64 v2, v[42:43], v[24:25] offset0:108 offset1:126
	ds_write_b64 v3, v[16:17]
	v_add_u32_e32 v3, 0x14400, v2
	ds_write_b64 v3, v[20:21]
	v_add_u32_e32 v3, 0x16800, v2
	ds_write_b64 v3, v[22:23]
	v_add_u32_e32 v3, 0x18c00, v2
	ds_write_b64 v3, v[32:33]
	v_add_u32_e32 v3, 0x1b000, v2
	ds_write_b64 v3, v[50:51]
	v_add_u32_e32 v3, 0x1d400, v2
	v_mov_b32_e32 v19, v5
	ds_write_b64 v3, v[64:65]
	v_add_u32_e32 v3, 0x1f800, v2
	v_add_u32_e32 v2, 0x21c00, v2
	ds_write_b64 v3, v[36:37]
	ds_write_b64 v2, v[18:19]
	s_cbranch_vccz .LBB0_637
; #define FFT_HD __device__ __attribute__((always_inline))
; template <int R> FFT_HD inline void reg_fwd(cf2 (&v)[1 << R], cf2 th) { dft_fwd_reg<R>(v); tw_apply<R, 1, false>(v, th, th); }
; template <int R, int F, bool CONJ> FFT_HD inline void tw_apply(cf2 (&v)[1 << R], cf2 pf, cf2 th) {
;     constexpr int j = fbrev(F, R);
;     v[j] = CONJ ? cmulcf(v[j], pf) : cmulf(v[j], pf);
;     if constexpr (2 * F < (1 << R)) {
;         const cf2 p2 = cmulf(pf, pf);
;         tw_apply<R, 2 * F, CONJ>(v, p2, th);
;         const cf2 p3 = cmulf(p2, th);
;         tw_apply<R, 2 * F + 1, CONJ>(v, p3, th);
;     }
; }
; __device__ __forceinline__ void s_mid2(ldsc X, const cf2* TW, int tid) {
; #pragma unroll 1
;     for (int q = 0; q < 2; ++q) { const int grp = tid + 512 * q; cf2 v[16]; grp_load<4, 64>(X, grp, v); reg_fwd<4>(v, TW[(grp & 63) * 16]); grp_store<4, 64>(X, grp, v); }
	v_lshlrev_b32_e32 v2, 7, v172
	v_and_b32_e32 v182, 0x1f80, v2
	s_waitcnt lgkmcnt(0)
	s_barrier
	global_load_dwordx2 v[36:37], v182, s[36:37]
	v_and_b32_e32 v173, 63, v172
	s_mov_b32 s3, 0
	v_lshl_add_u64 v[34:35], s[36:37], 0, v[182:183]
	s_mov_b64 s[4:5], -1
	s_waitcnt vmcnt(0)
	v_pk_mul_f32 v[2:3], v[36:37], v[36:37] op_sel:[1,1] op_sel_hi:[0,1]
	v_pk_fma_f32 v[4:5], v[36:37], v[36:37], v[2:3] op_sel_hi:[0,1,1] neg_lo:[0,0,1] neg_hi:[0,0,1]
	v_pk_fma_f32 v[2:3], v[36:37], v[36:37], v[2:3] op_sel_hi:[0,1,1]
	v_pk_mov_b32 v[42:43], v[2:3], v[4:5] op_sel:[1,0]
	v_pk_mul_f32 v[6:7], v[36:37], v[2:3] op_sel:[1,1] op_sel_hi:[0,1]
	v_mov_b32_e32 v40, v4
	v_mov_b32_e32 v41, v3
	v_pk_mul_f32 v[2:3], v[2:3], v[42:43] op_sel:[1,0]
	v_pk_fma_f32 v[8:9], v[36:37], v[4:5], v[6:7] op_sel_hi:[1,0,1] neg_lo:[0,0,1] neg_hi:[0,0,1]
	v_pk_fma_f32 v[6:7], v[36:37], v[4:5], v[6:7] op_sel_hi:[1,0,1]
	v_pk_fma_f32 v[10:11], v[4:5], v[40:41], v[2:3] op_sel_hi:[0,1,1] neg_lo:[0,0,1] neg_hi:[0,0,1]
	v_pk_fma_f32 v[2:3], v[4:5], v[40:41], v[2:3] op_sel_hi:[0,1,1]
	v_pk_mov_b32 v[46:47], v[6:7], v[8:9] op_sel:[1,0]
	v_mov_b32_e32 v44, v8
	v_mov_b32_e32 v45, v7
	v_pk_mov_b32 v[50:51], v[2:3], v[10:11] op_sel:[1,0]
	v_pk_mul_f32 v[4:5], v[36:37], v[10:11] op_sel_hi:[1,0]
	v_pk_mul_f32 v[6:7], v[6:7], v[46:47] op_sel:[1,0]
	v_mov_b32_e32 v48, v10
	v_mov_b32_e32 v49, v3
	v_pk_mul_f32 v[12:13], v[2:3], v[50:51] op_sel:[1,0]
	v_pk_fma_f32 v[14:15], v[36:37], v[2:3], v[4:5] op_sel:[0,1,1] op_sel_hi:[1,1,0] neg_lo:[1,0,0] neg_hi:[1,0,0]
	v_pk_fma_f32 v[2:3], v[36:37], v[2:3], v[4:5] op_sel:[0,1,1] op_sel_hi:[1,1,0]
	v_pk_fma_f32 v[4:5], v[8:9], v[44:45], v[6:7] op_sel_hi:[0,1,1] neg_lo:[0,0,1] neg_hi:[0,0,1]
	v_pk_fma_f32 v[6:7], v[8:9], v[44:45], v[6:7] op_sel_hi:[0,1,1]
	v_pk_fma_f32 v[8:9], v[10:11], v[48:49], v[12:13] op_sel_hi:[0,1,1] neg_lo:[0,0,1] neg_hi:[0,0,1]
	v_pk_fma_f32 v[10:11], v[10:11], v[48:49], v[12:13] op_sel_hi:[0,1,1]
	v_pk_mov_b32 v[12:13], v[14:15], v[2:3] op_sel:[1,0]
	v_pk_mov_b32 v[56:57], v[6:7], v[4:5] op_sel:[1,0]
	v_pk_mul_f32 v[16:17], v[36:37], v[6:7] op_sel:[1,1] op_sel_hi:[0,1]
	v_mov_b32_e32 v52, v2
	v_mov_b32_e32 v53, v15
	v_mov_b32_e32 v54, v4
	v_mov_b32_e32 v55, v7
	v_mov_b32_e32 v59, v11
	v_pk_mov_b32 v[60:61], v[10:11], v[8:9] op_sel:[1,0]
	v_pk_mul_f32 v[10:11], v[36:37], v[10:11] op_sel:[1,1] op_sel_hi:[0,1]
	v_pk_mul_f32 v[2:3], v[2:3], v[12:13] op_sel_hi:[0,1]
	v_pk_mul_f32 v[6:7], v[6:7], v[56:57] op_sel:[1,0]
	v_pk_fma_f32 v[12:13], v[36:37], v[4:5], v[16:17] op_sel_hi:[1,0,1] neg_lo:[0,0,1] neg_hi:[0,0,1]
	v_pk_fma_f32 v[16:17], v[36:37], v[4:5], v[16:17] op_sel_hi:[1,0,1]
	v_mov_b32_e32 v58, v8
	v_pk_fma_f32 v[18:19], v[36:37], v[8:9], v[10:11] op_sel_hi:[1,0,1] neg_lo:[0,0,1] neg_hi:[0,0,1]
	v_pk_fma_f32 v[8:9], v[36:37], v[8:9], v[10:11] op_sel_hi:[1,0,1]
	v_pk_fma_f32 v[10:11], v[14:15], v[52:53], v[2:3] op_sel:[1,0,0] neg_lo:[0,0,1] neg_hi:[0,0,1]
	v_pk_fma_f32 v[2:3], v[14:15], v[52:53], v[2:3] op_sel:[1,0,0]
	v_pk_fma_f32 v[14:15], v[4:5], v[54:55], v[6:7] op_sel_hi:[0,1,1] neg_lo:[0,0,1] neg_hi:[0,0,1]
	v_pk_fma_f32 v[4:5], v[4:5], v[54:55], v[6:7] op_sel_hi:[0,1,1]
	v_pk_mov_b32 v[64:65], v[16:17], v[12:13] op_sel:[1,0]
	v_mov_b32_e32 v62, v12
	v_mov_b32_e32 v63, v17
	v_mov_b32_e32 v68, v2
	v_pk_mul_f32 v[2:3], v[36:37], v[2:3] op_sel:[1,0] op_sel_hi:[0,0]
	v_mov_b32_e32 v71, v5
	v_pk_mov_b32 v[72:73], v[4:5], v[14:15] op_sel:[1,0]
	v_pk_mul_f32 v[4:5], v[36:37], v[4:5] op_sel:[1,1] op_sel_hi:[0,1]
	v_pk_mul_f32 v[6:7], v[16:17], v[64:65] op_sel:[1,0]
	v_mov_b32_e32 v67, v9
	v_mov_b32_e32 v69, v11
	v_mov_b32_e32 v70, v14
	v_pk_mov_b32 v[74:75], v[8:9], v[18:19] op_sel:[1,0]
	v_pk_fma_f32 v[8:9], v[36:37], v[10:11], v[2:3] op_sel:[0,1,0] neg_lo:[0,0,1] neg_hi:[0,0,1]
	v_pk_fma_f32 v[2:3], v[36:37], v[10:11], v[2:3] op_sel:[0,1,0]
	v_pk_fma_f32 v[10:11], v[36:37], v[14:15], v[4:5] op_sel_hi:[1,0,1] neg_lo:[0,0,1] neg_hi:[0,0,1]
	v_pk_fma_f32 v[4:5], v[36:37], v[14:15], v[4:5] op_sel_hi:[1,0,1]
	v_pk_fma_f32 v[14:15], v[12:13], v[62:63], v[6:7] op_sel_hi:[0,1,1] neg_lo:[0,0,1] neg_hi:[0,0,1]
	v_pk_fma_f32 v[6:7], v[12:13], v[62:63], v[6:7] op_sel_hi:[0,1,1]
	v_mov_b32_e32 v81, v7
	v_pk_mov_b32 v[82:83], v[6:7], v[14:15] op_sel:[1,0]
	v_pk_mul_f32 v[6:7], v[36:37], v[6:7] op_sel:[1,1] op_sel_hi:[0,1]
	v_mov_b32_e32 v77, v3
	v_mov_b32_e32 v79, v5
	v_pk_mov_b32 v[84:85], v[4:5], v[10:11] op_sel:[1,0]
	v_pk_mov_b32 v[86:87], v[2:3], v[8:9] op_sel:[1,0]
	v_pk_fma_f32 v[2:3], v[36:37], v[14:15], v[6:7] op_sel_hi:[1,0,1] neg_lo:[0,0,1] neg_hi:[0,0,1]
	v_pk_fma_f32 v[4:5], v[36:37], v[14:15], v[6:7] op_sel_hi:[1,0,1]
	v_pk_mov_b32 v[38:39], v[36:37], v[36:37] op_sel:[1,0]
	v_mov_b32_e32 v66, v18
	v_mov_b32_e32 v76, v8
	v_mov_b32_e32 v78, v10
	v_mov_b32_e32 v80, v14
	v_mov_b32_e32 v88, v2
	v_mov_b32_e32 v89, v5
	v_pk_mov_b32 v[90:91], v[4:5], v[2:3] op_sel:[1,0]

; __device__ __forceinline__ void hyena_conv_s2(const float* HYT, float* ZOUT, const float* FILT, const cf2* TW, LAS unsigned char* lds, int vb, int nb, int tid_in) {
;     ...
;         for (int q = 0; q < 2; ++q) { const int grp = tid + 512 * q; cf2 v[16]; float g1[8], fl[16];
; #pragma unroll
;             for (int m = 0; m < 16; ++m) { if (m < 8) g1[m] = hx1[grp + 1024 * m]; fl[m] = f1[grp + 1024 * m]; }
;             const cf2 th = TW[grp];
.LBB0_661:
	s_and_b64 vcc, exec, s[54:55]
	s_cbranch_vccz .Lcs2_b2
	v_cndmask_b32_e64 v2, 0, 1, s[54:55]
	v_cmp_ne_u32_e64 s[4:5], 1, v2
	v_add_u32_e32 v2, s3, v172
	v_ashrrev_i32_e32 v3, 31, v2
	v_lshlrev_b64 v[4:5], 2, v[2:3]
	v_lshl_add_u64 v[6:7], s[42:43], 0, v[4:5]
	v_add_co_u32_e32 v8, vcc, 0x1000, v6
	v_lshl_add_u64 v[4:5], s[50:51], 0, v[4:5]
	s_nop 0
	v_addc_co_u32_e32 v9, vcc, 0, v7, vcc
	global_load_dword v200, v[8:9], off offset:2048
	global_load_dword v10, v[8:9], off
	v_add_co_u32_e32 v8, vcc, 0x1000, v4
	global_load_dword v201, v[6:7], off offset:2048
	global_load_dword v42, v[6:7], off
	s_nop 0
	v_addc_co_u32_e32 v9, vcc, 0, v5, vcc
	global_load_dword v202, v[8:9], off offset:2048
	global_load_dword v11, v[8:9], off
	v_add_co_u32_e32 v8, vcc, s48, v6
	s_mov_b32 s83, s78
	s_nop 0
	v_addc_co_u32_e32 v9, vcc, 0, v7, vcc
	global_load_dword v203, v[8:9], off offset:2048
	global_load_dword v13, v[8:9], off
	v_add_co_u32_e32 v8, vcc, s48, v4
	s_mov_b32 s15, s60
	s_nop 0
	v_addc_co_u32_e32 v9, vcc, 0, v5, vcc
	global_load_dword v204, v[8:9], off offset:2048
	global_load_dword v12, v[8:9], off
	v_add_co_u32_e32 v8, vcc, 0x3000, v6
	s_mov_b32 s26, s61
	s_nop 0
	v_addc_co_u32_e32 v9, vcc, 0, v7, vcc
	global_load_dword v205, v[8:9], off offset:2048
	global_load_dword v15, v[8:9], off
	v_add_co_u32_e32 v8, vcc, 0x3000, v4
	s_mov_b32 s27, s60
	s_nop 0
	v_addc_co_u32_e32 v9, vcc, 0, v5, vcc
	global_load_dword v206, v[8:9], off offset:2048
	global_load_dword v14, v[8:9], off
	v_add_co_u32_e32 v8, vcc, s40, v6
	s_mov_b32 s85, s60
	s_nop 0
	v_addc_co_u32_e32 v9, vcc, 0, v7, vcc
	v_add_co_u32_e32 v18, vcc, s40, v4
	global_load_dword v207, v[8:9], off offset:-2048
	global_load_dword v45, v[8:9], off offset:-4096
	global_load_dword v208, v[4:5], off offset:2048
	global_load_dword v16, v[4:5], off
	v_addc_co_u32_e32 v19, vcc, 0, v5, vcc
	v_add_co_u32_e32 v6, vcc, s33, v6
	global_load_dword v209, v[18:19], off offset:-2048
	global_load_dword v199, v[18:19], off offset:-4096
	global_load_dword v210, v[8:9], off offset:2048
	global_load_dword v43, v[8:9], off
	global_load_dword v211, v[18:19], off offset:2048
	global_load_dword v17, v[18:19], off
	v_addc_co_u32_e32 v7, vcc, 0, v7, vcc
	v_add_co_u32_e32 v8, vcc, s33, v4
	global_load_dword v212, v[6:7], off offset:-2048
	global_load_dword v19, v[6:7], off offset:-4096
	s_nop 0
	v_addc_co_u32_e32 v9, vcc, 0, v5, vcc
	global_load_dword v213, v[8:9], off offset:-2048
	global_load_dword v18, v[8:9], off offset:-4096
	global_load_dword v214, v[6:7], off offset:2048
	global_load_dword v21, v[6:7], off
	global_load_dword v215, v[8:9], off offset:2048
	global_load_dword v20, v[8:9], off
	v_add_co_u32_e32 v6, vcc, s1, v4
	v_mov_b32_e32 v30, v183
	s_nop 0
	v_addc_co_u32_e32 v7, vcc, 0, v5, vcc
	global_load_dword v236, v[6:7], off offset:-2048
	global_load_dword v29, v[6:7], off offset:-4096
	global_load_dword v237, v[6:7], off offset:2048
	global_load_dword v27, v[6:7], off
	v_add_co_u32_e32 v6, vcc, s92, v4
	v_mov_b32_e32 v28, v183
	s_nop 0
	v_addc_co_u32_e32 v7, vcc, 0, v5, vcc
	global_load_dword v238, v[6:7], off offset:-2048
	global_load_dword v41, v[6:7], off offset:-4096
	global_load_dword v239, v[6:7], off offset:2048
	global_load_dword v25, v[6:7], off
	v_add_co_u32_e32 v6, vcc, s0, v4
	v_mov_b32_e32 v26, v183
	s_nop 0
	v_addc_co_u32_e32 v7, vcc, 0, v5, vcc
	v_add_co_u32_e32 v4, vcc, s18, v4
	global_load_dword v240, v[6:7], off offset:-2048
	global_load_dword v39, v[6:7], off offset:-4096
	global_load_dword v241, v[6:7], off offset:2048
	global_load_dword v31, v[6:7], off
	v_addc_co_u32_e32 v5, vcc, 0, v5, vcc
	global_load_dword v242, v[4:5], off offset:-2048
	global_load_dword v33, v[4:5], off offset:-4096
	global_load_dword v243, v[4:5], off offset:2048
	global_load_dword v23, v[4:5], off
	v_lshl_add_u64 v[4:5], v[2:3], 3, s[36:37]
	v_add_u32_e32 v246, 0x200, v2
	v_mov_b32_e32 v247, v3
	v_lshl_add_u64 v[246:247], v[246:247], 3, s[36:37]
	global_load_dwordx2 v[244:245], v[246:247], off
	global_load_dwordx2 v[6:7], v[4:5], off
	s_branch .Lcs2_bj
.Lcs2_b2:
	v_cndmask_b32_e64 v2, 0, 1, s[54:55]
	v_cmp_ne_u32_e64 s[4:5], 1, v2
	v_add_u32_e32 v2, s3, v172
	v_ashrrev_i32_e32 v3, 31, v2
	v_lshlrev_b64 v[4:5], 2, v[2:3]
	v_lshl_add_u64 v[6:7], s[42:43], 0, v[4:5]
	v_add_co_u32_e32 v8, vcc, 0x1000, v6
	v_lshl_add_u64 v[4:5], s[50:51], 0, v[4:5]
	s_nop 0
	v_addc_co_u32_e32 v9, vcc, 0, v7, vcc
	v_add_co_u32_e32 v8, vcc, 0x1000, v4
	s_nop 0
	v_addc_co_u32_e32 v9, vcc, 0, v5, vcc
	v_add_co_u32_e32 v8, vcc, s48, v6
	s_mov_b32 s83, s78
	s_nop 0
	v_addc_co_u32_e32 v9, vcc, 0, v7, vcc
	v_add_co_u32_e32 v8, vcc, s48, v4
	s_mov_b32 s15, s60
	s_nop 0
	v_addc_co_u32_e32 v9, vcc, 0, v5, vcc
	v_add_co_u32_e32 v8, vcc, 0x3000, v6
	s_mov_b32 s26, s61
	s_nop 0
	v_addc_co_u32_e32 v9, vcc, 0, v7, vcc
	v_add_co_u32_e32 v8, vcc, 0x3000, v4
	s_mov_b32 s27, s60
	s_nop 0
	v_addc_co_u32_e32 v9, vcc, 0, v5, vcc
	v_add_co_u32_e32 v8, vcc, s40, v6
	s_mov_b32 s85, s60
	s_nop 0
	v_addc_co_u32_e32 v9, vcc, 0, v7, vcc
	v_add_co_u32_e32 v18, vcc, s40, v4
	v_addc_co_u32_e32 v19, vcc, 0, v5, vcc
	v_add_co_u32_e32 v6, vcc, s33, v6
	v_addc_co_u32_e32 v7, vcc, 0, v7, vcc
	v_add_co_u32_e32 v8, vcc, s33, v4
	s_nop 0
	v_addc_co_u32_e32 v9, vcc, 0, v5, vcc
	v_add_co_u32_e32 v6, vcc, s1, v4
	v_mov_b32_e32 v30, v183
	s_nop 0
	v_addc_co_u32_e32 v7, vcc, 0, v5, vcc
	v_add_co_u32_e32 v6, vcc, s92, v4
	v_mov_b32_e32 v28, v183
	s_nop 0
	v_addc_co_u32_e32 v7, vcc, 0, v5, vcc
	v_add_co_u32_e32 v6, vcc, s0, v4
	v_mov_b32_e32 v26, v183
	s_nop 0
	v_addc_co_u32_e32 v7, vcc, 0, v5, vcc
	v_add_co_u32_e32 v4, vcc, s18, v4
	v_addc_co_u32_e32 v5, vcc, 0, v5, vcc
	v_lshl_add_u64 v[4:5], v[2:3], 3, s[36:37]
	s_waitcnt vmcnt(0)
	v_mov_b32_e32 v10, v200
	v_mov_b32_e32 v42, v201
	v_mov_b32_e32 v11, v202
	v_mov_b32_e32 v13, v203
	v_mov_b32_e32 v12, v204
	v_mov_b32_e32 v15, v205
	v_mov_b32_e32 v14, v206
	v_mov_b32_e32 v45, v207
	v_mov_b32_e32 v16, v208
	v_mov_b32_e32 v199, v209
	v_mov_b32_e32 v43, v210
	v_mov_b32_e32 v17, v211
	v_mov_b32_e32 v19, v212
	v_mov_b32_e32 v18, v213
	v_mov_b32_e32 v21, v214
	v_mov_b32_e32 v20, v215
	v_mov_b32_e32 v29, v236
	v_mov_b32_e32 v27, v237
	v_mov_b32_e32 v41, v238
	v_mov_b32_e32 v25, v239
	v_mov_b32_e32 v39, v240
	v_mov_b32_e32 v31, v241
	v_mov_b32_e32 v33, v242
	v_mov_b32_e32 v23, v243
	v_mov_b32_e32 v6, v244
	v_mov_b32_e32 v7, v245
; #define FFT_HD __device__ __attribute__((always_inline))
; template <int R> FFT_HD inline void reg_inv(cf2 (&v)[1 << R], cf2 th) { tw_apply<R, 1, true>(v, th, th); dft_inv_reg<R>(v); }
; template <int R, int F, bool CONJ> FFT_HD inline void tw_apply(cf2 (&v)[1 << R], cf2 pf, cf2 th) {
;     constexpr int j = fbrev(F, R);
;     v[j] = CONJ ? cmulcf(v[j], pf) : cmulf(v[j], pf);
;     if constexpr (2 * F < (1 << R)) {
;         const cf2 p2 = cmulf(pf, pf);
;         tw_apply<R, 2 * F, CONJ>(v, p2, th);
;         const cf2 p3 = cmulf(p2, th);
;         tw_apply<R, 2 * F + 1, CONJ>(v, p3, th);
;     }
; }
; template <int R, int S> FFT_HD inline int grp_base(int grp) { return (grp / S) * (S << R) + (grp & (S - 1)); }
; template <int R, int S, class P> FFT_HD inline void grp_load(P X, int grp, cf2 (&v)[1 << R]) {
;     P Xb = X + fpad(grp_base<R, S>(grp));
; #pragma unroll
;     for (int m = 0; m < (1 << R); ++m) v[m] = Xb[m * S + ((m * S) >> 3)];
; }
; __device__ __forceinline__ void hyena_conv_s2(const float* HYT, float* ZOUT, const float* FILT, const cf2* TW, LAS unsigned char* lds, int vb, int nb, int tid_in) {
;     ...
;         for (int q = 0; q < 2; ++q) { const int grp = tid + 512 * q; cf2 v[16]; float g1[8], fl[16];
; #pragma unroll
;             for (int m = 0; m < 16; ++m) { if (m < 8) g1[m] = hx1[grp + 1024 * m]; fl[m] = f1[grp + 1024 * m]; }
;             const cf2 th = TW[grp];
;             grp_load<4, 1024>(X, grp, v); reg_inv<4>(v, th);
.Lcs2_bj:
	v_lshrrev_b32_e32 v3, 22, v3
	v_add_lshl_u32 v3, v2, v3, 4
	v_and_b32_e32 v3, 0xffffc000, v3
	v_and_b32_e32 v2, 0x3ff, v2
	v_or_b32_e32 v4, v3, v2
	v_bitop3_b32 v2, v3, s19, v2 bitop3:0xc8
	v_lshlrev_b32_e32 v3, 3, v4
	v_add3_u32 v177, 0, v2, v3
	ds_read2st64_b64 v[46:49], v177 offset1:18
	ds_read2st64_b64 v[2:5], v177 offset0:36 offset1:54
	ds_read2st64_b64 v[50:53], v177 offset0:72 offset1:90
	ds_read2st64_b64 v[54:57], v177 offset0:108 offset1:126
	v_add_u32_e32 v182, 0x1b000, v177
	s_waitcnt lgkmcnt(3)
	v_mov_b32_e32 v60, v49
	s_waitcnt lgkmcnt(2)
	v_mov_b32_e32 v61, v5
	v_add_u32_e32 v185, 0x1d400, v177
	ds_read_b64 v[138:139], v182
	ds_read_b64 v[140:141], v185
	v_add_u32_e32 v189, 0x1f800, v177
	v_add_u32_e32 v198, 0x21c00, v177
	ds_read_b64 v[62:63], v189
	ds_read_b64 v[76:77], v198
	s_waitcnt lgkmcnt(3)
	v_mov_b32_e32 v98, v139
	s_waitcnt lgkmcnt(2)
	v_mov_b32_e32 v99, v141
	v_add_u32_e32 v178, 0x12000, v177
	v_add_u32_e32 v179, 0x14400, v177
	v_add_u32_e32 v180, 0x16800, v177
	v_add_u32_e32 v181, 0x18c00, v177
	ds_read_b64 v[8:9], v178
	ds_read_b64 v[72:73], v179
	ds_read_b64 v[78:79], v180
	ds_read_b64 v[80:81], v181
	v_mov_b32_e32 v40, v183
	v_mov_b32_e32 v24, v183
	v_mov_b32_e32 v38, v183
	v_mov_b32_e32 v32, v183
	s_mov_b32 s3, s80
	s_mov_b64 s[54:55], 0
	s_and_b64 vcc, exec, s[4:5]
	s_waitcnt vmcnt(0)
	v_pk_mul_f32 v[58:59], v[6:7], v[6:7] op_sel:[0,1] op_sel_hi:[1,0]
	v_mul_f32_e32 v22, v7, v7
	v_pk_add_f32 v[82:83], v[58:59], v[58:59]
	v_pk_fma_f32 v[74:75], v[6:7], v[6:7], v[22:23] op_sel_hi:[1,1,0] neg_lo:[0,0,1] neg_hi:[0,0,1]
	v_mov_b32_e32 v58, v48
	v_pk_mul_f32 v[48:49], v[6:7], v[82:83] op_sel:[1,0] op_sel_hi:[0,0]
	v_pk_fma_f32 v[84:85], v[6:7], v[74:75], v[48:49] op_sel_hi:[1,0,1]
	v_pk_mul_f32 v[136:137], v[82:83], v[50:51]
	v_pk_fma_f32 v[142:143], v[6:7], v[74:75], v[48:49] op_sel_hi:[1,0,1] neg_lo:[0,0,1] neg_hi:[0,0,1]
	v_mov_b32_e32 v83, v85
	v_pk_mul_f32 v[134:135], v[74:75], v[50:51] op_sel:[0,1] op_sel_hi:[1,0]
	v_mov_b32_e32 v75, v142
	v_pk_mul_f32 v[48:49], v[82:83], v[82:83]
	v_mov_b32_e32 v59, v4
	v_pk_fma_f32 v[66:67], v[74:75], v[74:75], v[48:49] neg_lo:[0,0,1] neg_hi:[0,0,1]
	v_pk_mul_f32 v[48:49], v[74:75], v[82:83]
	v_mul_f32_e32 v22, v2, v66
	v_pk_add_f32 v[86:87], v[48:49], v[48:49]
	v_mov_b32_e32 v48, v66
	v_mov_b32_e32 v49, v86
	v_pk_mul_f32 v[64:65], v[66:67], v[86:87]
	v_pk_fma_f32 v[88:89], v[2:3], v[48:49], v[22:23] op_sel_hi:[1,1,0]
	v_pk_mul_f32 v[48:49], v[86:87], v[86:87]
	v_pk_add_f32 v[64:65], v[64:65], v[64:65]
	v_pk_fma_f32 v[48:49], v[66:67], v[66:67], v[48:49] neg_lo:[0,0,1] neg_hi:[0,0,1]
	v_pk_mul_f32 v[60:61], v[60:61], v[64:65]
	v_mov_b32_e32 v143, v85
	v_pk_fma_f32 v[58:59], v[58:59], v[48:49], v[60:61]
	v_mov_b32_e32 v84, v138
	v_pk_add_f32 v[60:61], v[46:47], v[58:59] neg_lo:[0,1] neg_hi:[0,1]
	v_mov_b32_e32 v47, v89
	v_pk_add_f32 v[58:59], v[46:47], v[58:59]
	v_pk_mul_f32 v[46:47], v[6:7], v[86:87] op_sel:[1,0]
	v_pk_mul_f32 v[88:89], v[6:7], v[86:87] op_sel_hi:[0,1]
	v_pk_fma_f32 v[46:47], v[6:7], v[66:67], v[46:47] op_sel_hi:[0,1,1] neg_lo:[0,0,1] neg_hi:[0,0,1]
	v_pk_fma_f32 v[88:89], v[6:7], v[66:67], v[88:89] op_sel:[1,0,0]
	v_mov_b32_e32 v90, v87
	v_pk_mul_f32 v[94:95], v[46:47], v[88:89]
	v_pk_mul_f32 v[92:93], v[88:89], v[88:89]
	v_pk_add_f32 v[94:95], v[94:95], v[94:95]
	v_pk_fma_f32 v[92:93], v[46:47], v[46:47], v[92:93] neg_lo:[0,0,1] neg_hi:[0,0,1]
	v_pk_mul_f32 v[96:97], v[6:7], v[94:95] op_sel:[1,0] op_sel_hi:[0,0]
	v_pk_fma_f32 v[158:159], v[6:7], v[92:93], v[96:97] op_sel_hi:[1,0,1]
	v_pk_fma_f32 v[154:155], v[6:7], v[92:93], v[96:97] op_sel_hi:[1,0,1] neg_lo:[0,0,1] neg_hi:[0,0,1]
	v_mov_b32_e32 v158, v85
	v_mov_b32_e32 v85, v140
	v_mov_b32_e32 v91, v67
	v_mov_b32_e32 v96, v142
	v_mov_b32_e32 v97, v154
	v_pk_mul_f32 v[84:85], v[158:159], v[84:85]
	v_pk_mul_f32 v[90:91], v[90:91], v[54:55]
	v_pk_fma_f32 v[84:85], v[96:97], v[98:99], v[84:85] neg_lo:[0,0,1] neg_hi:[0,0,1]
	v_mov_b32_e32 v97, v54
	v_mov_b32_e32 v83, v87
	v_mov_b32_e32 v54, v51
	v_mov_b32_e32 v75, v67
	v_mov_b32_e32 v96, v50
	v_pk_mul_f32 v[50:51], v[82:83], v[54:55]
	v_pk_mul_f32 v[146:147], v[52:53], v[92:93] op_sel:[1,0] op_sel_hi:[0,1]
	v_pk_fma_f32 v[144:145], v[74:75], v[96:97], v[50:51]
	v_mov_b32_e32 v50, v89
	v_mov_b32_e32 v51, v47
	v_pk_mul_f32 v[150:151], v[52:53], v[94:95]
	s_waitcnt lgkmcnt(5)
	v_pk_mul_f32 v[160:161], v[50:51], v[62:63]
	v_mov_b32_e32 v50, v52
	v_mov_b32_e32 v52, v53
	v_mov_b32_e32 v53, v57
	v_mov_b32_e32 v51, v56
	v_pk_mul_f32 v[52:53], v[52:53], v[94:95]
	v_pk_mul_f32 v[54:55], v[6:7], v[94:95] op_sel:[0,1]
	v_pk_fma_f32 v[152:153], v[50:51], v[92:93], v[52:53]
	v_mov_b32_e32 v50, v95
	v_mov_b32_e32 v51, v93
	v_pk_mul_f32 v[50:51], v[56:57], v[50:51]
	v_mov_b32_e32 v52, v91
	v_mov_b32_e32 v53, v51
	v_mov_b32_e32 v91, v50
	v_pk_fma_f32 v[56:57], v[6:7], v[92:93], v[54:55] op_sel:[1,1,0] op_sel_hi:[0,1,1] neg_lo:[0,0,1] neg_hi:[0,0,1]
	v_pk_fma_f32 v[54:55], v[6:7], v[92:93], v[54:55] op_sel:[1,1,0] op_sel_hi:[0,1,1]
	v_pk_add_f32 v[156:157], v[52:53], v[90:91] neg_lo:[0,1] neg_hi:[0,1]
	v_mov_b32_e32 v52, v63
	s_waitcnt lgkmcnt(4)
	v_mov_b32_e32 v53, v77
	v_mov_b32_e32 v56, v54
	v_pk_mov_b32 v[54:55], v[88:89], v[54:55] op_sel:[1,0]
	v_pk_mul_f32 v[70:71], v[2:3], v[86:87]
	v_mov_b32_e32 v50, v62
	v_mov_b32_e32 v51, v76
	v_mov_b32_e32 v62, v47
	v_mov_b32_e32 v63, v57
	v_pk_mul_f32 v[52:53], v[54:55], v[52:53]
	v_mul_f32_e32 v22, v57, v77
	s_waitcnt lgkmcnt(0)
; #define FFT_HD __device__ __attribute__((always_inline))
; template <int R> FFT_HD inline void dft_inv_reg(cf2 (&v)[1 << R]) {
;     constexpr int n = 1 << R;
; #pragma unroll
;     for (int s = R - 1; s >= 0; --s) {
;         const int half = n >> (s + 1);
; #pragma unroll
;         for (int m = 0; m < n; ++m) {
;             if ((m & half) == 0) {
;                 const int ml = m & (half - 1), tk = ml * (16 / half);
;                 const cf2 a = v[m], bb = v[m + half]; cf2 b;
;                 if (tk == 0) b = bb;
;                 else if (tk == 8) { b.x = -bb.y; b.y = bb.x; }
;                 else { const cf2 w = {fc32(tk), -fs32(tk)}; b = cmulcf(bb, w); }
;                 v[m].x = a.x + b.x; v[m].y = a.y + b.y; v[m + half].x = a.x - b.x; v[m + half].y = a.y - b.y;
;             }
;         }
;     }
; }
	v_mov_b32_e32 v83, v80
	v_mov_b32_e32 v80, v73
	v_mov_b32_e32 v73, v78
	v_pk_mov_b32 v[86:87], v[6:7], v[88:89] op_sel:[1,0]
	v_mov_b32_e32 v78, v9
	v_pk_mul_f32 v[148:149], v[142:143], v[138:139]
	v_mov_b32_e32 v155, v159
	v_pk_fma_f32 v[74:75], v[62:63], v[50:51], v[52:53]
	v_pk_fma_f32 v[76:77], v[56:57], v[76:77], v[22:23] op_sel_hi:[1,1,0] neg_lo:[1,0,0] neg_hi:[1,0,0]
	v_pk_mul_f32 v[52:53], v[6:7], v[64:65] op_sel_hi:[0,1]
	v_mov_b32_e32 v82, v72
	v_mov_b32_e32 v56, v6
	v_mov_b32_e32 v57, v46
	v_mov_b32_e32 v72, v8
	v_pk_mul_f32 v[8:9], v[86:87], v[78:79]
	v_mul_f32_e32 v44, v159, v141
	v_pk_mul_f32 v[50:51], v[6:7], v[64:65] op_sel:[1,0]
	v_pk_fma_f32 v[54:55], v[6:7], v[48:49], v[52:53] op_sel:[1,0,0]
	v_pk_fma_f32 v[166:167], v[56:57], v[72:73], v[8:9]
	v_pk_mul_f32 v[8:9], v[86:87], v[72:73]
	v_pk_fma_f32 v[140:141], v[154:155], v[140:141], v[44:45] op_sel_hi:[1,1,0]
	v_mov_b32_e32 v154, v148
	v_mov_b32_e32 v155, v161
	v_pk_mov_b32 v[148:149], v[148:149], v[160:161] op_sel:[1,0]
	v_pk_fma_f32 v[50:51], v[6:7], v[48:49], v[50:51] op_sel_hi:[0,1,1] neg_lo:[0,0,1] neg_hi:[0,0,1]
	v_pk_mul_f32 v[52:53], v[54:55], v[80:81]
	v_pk_fma_f32 v[56:57], v[56:57], v[78:79], v[8:9] neg_lo:[0,0,1] neg_hi:[0,0,1]
	v_pk_mul_f32 v[8:9], v[54:55], v[82:83]
	v_pk_fma_f32 v[138:139], v[142:143], v[138:139], v[148:149]
	v_pk_add_f32 v[158:159], v[154:155], v[148:149] neg_lo:[0,1] neg_hi:[0,1]
	v_pk_fma_f32 v[164:165], v[50:51], v[82:83], v[52:53]
	v_pk_fma_f32 v[168:169], v[50:51], v[80:81], v[8:9] neg_lo:[0,0,1] neg_hi:[0,0,1]
	v_mov_b32_e32 v8, v84
	v_mov_b32_e32 v9, v74
	v_mov_b32_e32 v50, v85
	v_mov_b32_e32 v51, v75
	v_mov_b32_e32 v139, v159
	v_mov_b32_e32 v141, v76
	v_pk_add_f32 v[170:171], v[8:9], v[50:51] neg_lo:[0,1] neg_hi:[0,1]
	v_pk_add_f32 v[142:143], v[138:139], v[140:141] neg_lo:[0,1] neg_hi:[0,1]
	v_pk_add_f32 v[148:149], v[170:171], v[170:171] op_sel:[0,1] op_sel_hi:[1,0]
	v_pk_add_f32 v[154:155], v[142:143], v[142:143] op_sel_hi:[0,1] neg_lo:[0,1] neg_hi:[0,1]
	v_pk_add_f32 v[46:47], v[166:167], v[164:165] neg_lo:[0,1] neg_hi:[0,1]
	v_pk_add_f32 v[78:79], v[56:57], v[168:169] neg_lo:[0,1] neg_hi:[0,1]
	v_mov_b32_e32 v149, v155
	v_mov_b32_e32 v135, v56
	v_mov_b32_e32 v137, v168
	v_pk_add_f32 v[80:81], v[56:57], v[168:169]
	v_pk_mul_f32 v[154:155], v[148:149], s[80:81] op_sel_hi:[1,0]
	v_pk_add_f32 v[168:169], v[134:135], v[136:137] neg_lo:[0,1] neg_hi:[0,1]
	v_mov_b32_e32 v147, v167
	v_mov_b32_e32 v151, v165
	v_mov_b32_e32 v136, v144
	v_mov_b32_e32 v137, v46
	v_mov_b32_e32 v78, v152
	v_pk_mul_f32 v[68:69], v[2:3], v[66:67] op_sel:[1,0] op_sel_hi:[0,1]
	v_pk_add_f32 v[52:53], v[166:167], v[164:165]
	v_pk_add_f32 v[72:73], v[170:171], v[170:171] op_sel_hi:[0,1] neg_lo:[0,1] neg_hi:[0,1]
	v_pk_fma_f32 v[170:171], v[148:149], s[80:81], v[154:155] op_sel:[0,0,1] op_sel_hi:[1,0,0]
	v_pk_add_f32 v[164:165], v[146:147], v[150:151] neg_lo:[0,1] neg_hi:[0,1]
	v_pk_add_f32 v[146:147], v[136:137], v[78:79] neg_lo:[0,1] neg_hi:[0,1]
	v_mov_b32_e32 v136, v156
	v_mov_b32_e32 v137, v155
	v_pk_mov_b32 v[148:149], v[156:157], v[154:155] op_sel:[1,0]
	v_pk_add_f32 v[142:143], v[142:143], v[142:143] op_sel:[0,1] op_sel_hi:[1,0]
	v_pk_add_f32 v[166:167], v[168:169], v[164:165]
	v_pk_add_f32 v[150:151], v[136:137], v[148:149] neg_lo:[0,1] neg_hi:[0,1]
	v_pk_add_f32 v[148:149], v[168:169], v[164:165] neg_lo:[0,1] neg_hi:[0,1]
	v_mov_b32_e32 v168, v145
	v_mov_b32_e32 v164, v153
	v_mov_b32_e32 v69, v46
	v_mov_b32_e32 v78, v70
	v_mov_b32_e32 v72, v4
	v_mov_b32_e32 v186, v65
	v_pk_add_f32 v[62:63], v[144:145], v[152:153]
	v_pk_add_f32 v[144:145], v[168:169], v[164:165] neg_lo:[0,1] neg_hi:[0,1]
	v_pk_fma_f32 v[2:3], v[2:3], v[66:67], v[70:71] op_sel:[1,0,0] op_sel_hi:[0,1,1] neg_lo:[0,0,1] neg_hi:[0,0,1]
	v_pk_add_f32 v[66:67], v[68:69], v[78:79]
	v_pk_mul_f32 v[68:69], v[72:73], v[186:187]
	v_pk_mov_b32 v[4:5], v[4:5], v[142:143] op_sel:[1,0]
	v_mov_b32_e32 v70, v49
	v_mov_b32_e32 v71, v188
	v_mov_b32_e32 v135, v166
	v_mov_b32_e32 v166, v148
	v_mov_b32_e32 v152, v144
	v_mov_b32_e32 v153, v170
	v_mov_b32_e32 v3, v67
	v_pk_fma_f32 v[4:5], v[4:5], v[70:71], v[68:69] neg_lo:[0,0,1] neg_hi:[0,0,1]
	v_mov_b32_e32 v139, v43
	v_pk_add_f32 v[154:155], v[146:147], v[150:151] neg_lo:[0,1] neg_hi:[0,1]
	v_pk_add_f32 v[160:161], v[146:147], v[150:151]
	v_sub_f32_e32 v43, v167, v170
	v_pk_add_f32 v[152:153], v[166:167], v[152:153]
	v_pk_add_f32 v[2:3], v[2:3], v[4:5] neg_lo:[0,1] neg_hi:[0,1]
	v_pk_add_f32 v[162:163], v[156:157], v[156:157] op_sel_hi:[0,1]
	v_mov_b32_e32 v160, v154
	s_mov_b32 s81, s61
	v_mul_f32_e32 v155, 0xbec3ef15, v155
	v_mul_f32_e32 v157, 0x3f6c835e, v43
	v_mov_b32_e32 v154, v60
	v_pk_mul_f32 v[152:153], v[152:153], s[82:83]
	v_mov_b32_e32 v156, v2
	v_mov_b32_e32 v190, v60
	v_sub_f32_e32 v9, v11, v27
	v_pk_fma_f32 v[152:153], v[160:161], s[80:81], v[152:153]
	v_pk_add_f32 v[72:73], v[154:155], v[156:157] neg_lo:[0,1] neg_hi:[0,1]
	v_pk_add_f32 v[60:61], v[2:3], v[60:61]
	v_pk_mul_f32 v[2:3], v[2:3], v[190:191]
	v_pk_add_f32 v[50:51], v[80:81], v[80:81] op_sel_hi:[0,1]
	v_mov_b32_e32 v8, v6
	v_mul_f32_e32 v6, 0x3ec3ef15, v9
	v_mul_f32_e32 v64, 0x3f6c835e, v9
	v_sub_f32_e32 v9, v17, v31
	v_fma_f32 v69, v142, s80, -v69
	v_mov_b32_e32 v68, v148
	v_sub_f32_e32 v2, v72, v152
	v_mul_f32_e32 v57, 0x3f6c835e, v9
	v_mul_f32_e32 v50, 0xbec3ef15, v9
	v_mov_b32_e32 v9, v7
	v_mov_b32_e32 v147, v67
	v_pk_add_f32 v[66:67], v[148:149], v[144:145] neg_lo:[0,1] neg_hi:[0,1]
	v_pk_add_f32 v[70:71], v[68:69], v[144:145]
	v_mov_b32_e32 v61, v3
	v_pk_add_f32 v[2:3], v[2:3], v[72:73] op_sel_hi:[0,1]
	v_pk_add_f32 v[54:55], v[84:85], v[84:85] op_sel:[0,1] op_sel_hi:[1,0]
; #define FFT_HD __device__ __attribute__((always_inline))
; template <int R> FFT_HD inline void reg_fwd(cf2 (&v)[1 << R], cf2 th) { dft_fwd_reg<R>(v); tw_apply<R, 1, false>(v, th, th); }
; __device__ __forceinline__ cf2 tw_fresh(cf2 th) { asm volatile("" : "+v"(th.x), "+v"(th.y)); return th; }
; template <int R> FFT_HD inline void dft_inv_reg(cf2 (&v)[1 << R]) {
;     constexpr int n = 1 << R;
; #pragma unroll
;     for (int s = R - 1; s >= 0; --s) {
;         const int half = n >> (s + 1);
; #pragma unroll
;         for (int m = 0; m < n; ++m) {
;             if ((m & half) == 0) {
;                 const int ml = m & (half - 1), tk = ml * (16 / half);
;                 const cf2 a = v[m], bb = v[m + half]; cf2 b;
;                 if (tk == 0) b = bb;
;                 else if (tk == 8) { b.x = -bb.y; b.y = bb.x; }
;                 else { const cf2 w = {fc32(tk), -fs32(tk)}; b = cmulcf(bb, w); }
;                 v[m].x = a.x + b.x; v[m].y = a.y + b.y; v[m + half].x = a.x - b.x; v[m + half].y = a.y - b.y;
;             }
;         }
;     }
; }
; __device__ __forceinline__ void hyena_conv_s2(const float* HYT, float* ZOUT, const float* FILT, const cf2* TW, LAS unsigned char* lds, int vb, int nb, int tid_in) {
;     ...
; #pragma unroll
;             for (int m = 0; m < 16; ++m) { v[m].x = m < 8 ? v[m].x * g1[m] : 0.f; v[m].y = fl[m]; }
;             reg_fwd<4>(v, tw_fresh(th)); grp_store<4, 1024>(X, grp, v); }
	v_pk_mul_f32 v[82:83], v[8:9], v[8:9]
	v_mul_f32_e32 v85, v8, v7
	v_mov_b32_e32 v151, v5
	v_mov_b32_e32 v67, v71
	v_mov_b32_e32 v141, v3
	v_mov_b32_e32 v84, v82
	v_mov_b32_e32 v82, v83
	v_mov_b32_e32 v83, v85
	v_pk_mov_b32 v[158:159], v[158:159], v[74:75] op_sel:[1,0]
	v_mov_b32_e32 v77, v75
	v_pk_add_f32 v[4:5], v[146:147], v[150:151]
	s_mov_b32 s83, s60
	v_pk_mul_f32 v[66:67], v[66:67], s[80:81]
	v_pk_add_f32 v[70:71], v[138:139], v[140:141]
	v_pk_add_f32 v[88:89], v[84:85], v[82:83] neg_lo:[0,1] neg_hi:[0,1]
	v_pk_add_f32 v[82:83], v[84:85], v[82:83]
	v_pk_add_f32 v[74:75], v[158:159], v[76:77]
	v_mov_b32_e32 v76, v52
	v_mov_b32_e32 v77, v80
	v_mov_b32_e32 v80, v53
	v_pk_fma_f32 v[4:5], v[4:5], s[82:83], v[66:67] neg_lo:[0,0,1] neg_hi:[0,0,1]
	v_mov_b32_e32 v66, v54
	v_mov_b32_e32 v67, v70
	v_mov_b32_e32 v162, v59
	v_mov_b32_e32 v86, v88
	v_mov_b32_e32 v87, v83
	v_mov_b32_e32 v134, v58
	v_pk_add_f32 v[76:77], v[76:77], v[80:81] neg_lo:[0,1] neg_hi:[0,1]
	v_add_f32_e32 v44, v72, v152
	v_pk_add_f32 v[66:67], v[66:67], v[74:75] neg_lo:[0,1] neg_hi:[0,1]
	v_pk_mul_f32 v[90:91], v[86:87], v[86:87]
	v_pk_mul_f32 v[92:93], v[86:87], v[82:83] op_sel:[0,1] op_sel_hi:[1,0]
	v_pk_add_f32 v[134:135], v[134:135], v[162:163] neg_lo:[0,1] neg_hi:[0,1]
	v_pk_mul_f32 v[2:3], v[138:139], v[140:141]
	v_sub_f32_e32 v43, v145, v69
	v_add_f32_e32 v46, v44, v153
	v_add_f32_e32 v44, v60, v4
	v_pk_add_f32 v[68:69], v[76:77], v[66:67] neg_lo:[0,1] neg_hi:[0,1]
	v_pk_add_f32 v[66:67], v[76:77], v[66:67]
	v_mov_b32_e32 v94, v90
	v_mov_b32_e32 v95, v92
	v_pk_mov_b32 v[90:91], v[90:91], v[92:93] op_sel:[1,0]
	v_mov_b32_e32 v71, v3
	v_pk_add_f32 v[72:73], v[44:45], v[4:5] op_sel_hi:[0,1]
	v_mul_f32_e32 v79, 0x3f3504f3, v68
	v_mov_b32_e32 v68, v66
	v_mul_f32_e32 v67, 0x3f3504f3, v67
	v_mov_b32_e32 v78, v134
	v_mov_b32_e32 v66, v135
	v_mul_f32_e32 v5, 0x3ec3ef15, v43
	v_mov_b32_e32 v192, v75
	v_pk_add_f32 v[92:93], v[94:95], v[90:91] neg_lo:[0,1] neg_hi:[0,1]
	v_pk_add_f32 v[122:123], v[94:95], v[90:91]
	v_pk_add_f32 v[66:67], v[78:79], v[66:67] neg_lo:[0,1] neg_hi:[0,1]
	s_mov_b32 s83, s80
	v_mul_f32_e32 v44, 0x3f3504f3, v69
	v_pk_add_f32 v[4:5], v[60:61], v[4:5] neg_lo:[0,1] neg_hi:[0,1]
	v_mul_f32_e32 v10, v10, v46
	v_pk_add_f32 v[70:71], v[70:71], v[192:193]
	v_pk_mul_f32 v[138:139], v[2:3], s[14:15]
	v_pk_add_f32 v[52:53], v[52:53], v[52:53] op_sel:[0,1] op_sel_hi:[1,0]
	v_pk_mov_b32 v[54:55], v[2:3], v[54:55] op_sel:[1,0]
	v_mov_b32_e32 v126, v92
	v_mov_b32_e32 v127, v123
	v_pk_add_f32 v[136:137], v[134:135], v[134:135] op_sel:[0,1] op_sel_hi:[1,0]
	v_add_f32_e32 v49, v66, v67
	v_pk_fma_f32 v[66:67], v[68:69], s[82:83], v[44:45] op_sel_hi:[1,1,0] neg_lo:[0,0,1] neg_hi:[0,0,1]
	v_pk_add_f32 v[76:77], v[4:5], v[4:5] op_sel_hi:[0,1]
	v_mul_f32_e32 v5, 0x3f6c835e, v10
	v_pk_add_f32 v[58:59], v[58:59], v[58:59] op_sel:[0,1] op_sel_hi:[1,0]
	v_pk_add_f32 v[60:61], v[62:63], v[62:63] op_sel:[0,1] op_sel_hi:[1,0]
	v_mov_b32_e32 v138, v70
	v_mov_b32_e32 v56, v52
	v_pk_add_f32 v[52:53], v[52:53], v[70:71]
	v_pk_mul_f32 v[70:71], v[54:55], s[26:27]
	v_pk_add_f32 v[54:55], v[54:55], v[74:75] op_sel_hi:[1,0]
	v_pk_mul_f32 v[90:91], v[126:127], v[122:123] op_sel:[0,1] op_sel_hi:[1,0]
	v_pk_add_f32 v[66:67], v[136:137], v[66:67]
	v_mov_b32_e32 v59, v6
	v_mov_b32_e32 v61, v5
	v_mul_f32_e32 v62, 0x3ec3ef15, v10
	v_mov_b32_e32 v65, v58
	v_mov_b32_e32 v63, v60
	v_mov_b32_e32 v76, v23
	v_pk_add_f32 v[56:57], v[56:57], v[138:139] neg_lo:[0,1] neg_hi:[0,1]
	v_mov_b32_e32 v71, v55
	v_pk_add_f32 v[120:121], v[90:91], v[90:91]
	v_pk_mul_f32 v[90:91], v[8:9], v[122:123] op_sel:[1,1] op_sel_hi:[0,1]
	v_pk_add_f32 v[68:69], v[58:59], v[60:61]
	v_pk_add_f32 v[60:61], v[64:65], v[62:63] neg_lo:[0,1] neg_hi:[0,1]
	v_pk_add_f32 v[64:65], v[20:21], v[76:77] neg_lo:[0,1] neg_hi:[0,1]
	v_pk_mul_f32 v[58:59], v[20:21], v[76:77]
	v_mov_b32_e32 v72, v25
	v_mov_b32_e32 v53, v57
	v_pk_add_f32 v[54:55], v[50:51], v[70:71] neg_lo:[0,1] neg_hi:[0,1]
	v_mov_b32_e32 v50, v33
	v_mov_b32_e32 v51, v66
	v_pk_fma_f32 v[94:95], v[8:9], v[92:93], v[90:91] op_sel_hi:[1,0,1] neg_lo:[0,0,1] neg_hi:[0,0,1]
	v_pk_fma_f32 v[114:115], v[8:9], v[92:93], v[90:91] op_sel_hi:[1,0,1]
	v_pk_mul_f32 v[90:91], v[8:9], v[82:83] op_sel:[1,1] op_sel_hi:[0,1]
	v_mov_b32_e32 v65, v59
	v_mul_f32_e32 v6, 0x3ec3ef15, v59
	v_pk_add_f32 v[136:137], v[14:15], v[72:73] neg_lo:[0,1] neg_hi:[0,1]
	v_pk_mul_f32 v[72:73], v[14:15], v[72:73]
	v_pk_add_f32 v[70:71], v[18:19], v[50:51] neg_lo:[0,1] neg_hi:[0,1]
	v_pk_mul_f32 v[74:75], v[18:19], v[50:51]
	v_pk_add_f32 v[50:51], v[68:69], v[52:53]
	v_pk_add_f32 v[52:53], v[68:69], v[56:57] neg_lo:[0,1] neg_hi:[0,1]
	v_pk_mov_b32 v[124:125], v[122:123], v[92:93] op_sel:[1,0]
	v_pk_fma_f32 v[92:93], v[8:9], v[88:89], v[90:91] op_sel_hi:[1,0,1] neg_lo:[0,0,1] neg_hi:[0,0,1]
	v_pk_fma_f32 v[102:103], v[8:9], v[88:89], v[90:91] op_sel_hi:[1,0,1]
	v_mul_f32_e32 v4, v13, v49
	v_pk_fma_f32 v[76:77], v[64:65], s[84:85], v[6:7] op_sel_hi:[1,1,0] neg_lo:[0,0,1] neg_hi:[0,0,1]
	v_mul_f32_e32 v13, 0x3ec3ef15, v136
	v_mul_f32_e32 v81, 0x3f6c835e, v73
	v_mov_b32_e32 v80, v41
	v_mov_b32_e32 v52, v50
	v_mov_b32_e32 v43, v187
	v_pk_add_f32 v[68:69], v[60:61], v[54:55] neg_lo:[0,1] neg_hi:[0,1]
	v_mov_b32_e32 v44, v187
	v_mov_b32_e32 v110, v92
	v_mov_b32_e32 v111, v103
	v_mov_b32_e32 v78, v187
	v_mov_b32_e32 v79, v76
	v_pk_add_f32 v[80:81], v[12:13], v[80:81] neg_lo:[0,1] neg_hi:[0,1]
	v_pk_mul_f32 v[56:57], v[42:43], v[52:53]
	v_pk_mul_f32 v[142:143], v[44:45], v[68:69]
	v_sub_f32_e32 v47, v16, v29
	v_pk_mov_b32 v[84:85], v[82:83], v[88:89] op_sel:[1,0]
	v_pk_mul_f32 v[88:89], v[110:111], v[110:111]
; #define FFT_HD __device__ __attribute__((always_inline))
; template <int R> FFT_HD inline void reg_fwd(cf2 (&v)[1 << R], cf2 th) { dft_fwd_reg<R>(v); tw_apply<R, 1, false>(v, th, th); }
; __device__ __forceinline__ cf2 tw_fresh(cf2 th) { asm volatile("" : "+v"(th.x), "+v"(th.y)); return th; }
; template <int R> FFT_HD inline void dft_fwd_reg(cf2 (&v)[1 << R]) {
;     constexpr int n = 1 << R;
; #pragma unroll
;     for (int s = 0; s < R; ++s) {
;         const int half = n >> (s + 1);
; #pragma unroll
;         for (int m = 0; m < n; ++m) {
;             if ((m & half) == 0) {
;                 const int ml = m & (half - 1), tk = ml * (16 / half);
;                 const cf2 a = v[m], b = v[m + half];
;                 v[m].x = a.x + b.x; v[m].y = a.y + b.y;
;                 const cf2 d = {a.x - b.x, a.y - b.y};
;                 if (tk == 0) v[m + half] = d;
;                 else if (tk == 8) { v[m + half].x = d.y; v[m + half].y = -d.x; }
;                 else { const cf2 w = {fc32(tk), -fs32(tk)}; v[m + half] = cmulf(d, w); }
;             }
;         }
;     }
; }
; __device__ __forceinline__ void hyena_conv_s2(const float* HYT, float* ZOUT, const float* FILT, const cf2* TW, LAS unsigned char* lds, int vb, int nb, int tid_in) {
;     ...
; #pragma unroll
;             for (int m = 0; m < 16; ++m) { v[m].x = m < 8 ? v[m].x * g1[m] : 0.f; v[m].y = fl[m]; }
;             reg_fwd<4>(v, tw_fresh(th)); grp_store<4, 1024>(X, grp, v); }
	v_pk_mul_f32 v[90:91], v[110:111], v[102:103] op_sel:[0,1] op_sel_hi:[1,0]
	v_pk_mul_f32 v[134:135], v[80:81], v[78:79]
	v_mul_f32_e32 v2, 0x3f6c835e, v59
	v_pk_mov_b32 v[144:145], v[142:143], v[142:143] op_sel:[1,0]
	v_mov_b32_e32 v46, v57
	v_mov_b32_e32 v57, v16
	v_mov_b32_e32 v16, v3
	v_sub_f32_e32 v48, v199, v39
	v_mov_b32_e32 v22, v183
	v_pk_mov_b32 v[112:113], v[102:103], v[92:93] op_sel:[1,0]
	v_mov_b32_e32 v92, v88
	v_mov_b32_e32 v93, v90
	v_pk_mov_b32 v[88:89], v[88:89], v[90:91] op_sel:[1,0]
	v_mov_b32_e32 v67, v134
	v_pk_fma_f32 v[64:65], v[64:65], s[60:61], v[2:3] op_sel_hi:[1,1,0] neg_lo:[0,0,1] neg_hi:[0,0,1]
	v_mov_b32_e32 v49, v145
	v_mov_b32_e32 v5, v12
	v_mov_b32_e32 v12, v73
	v_mov_b32_e32 v13, v14
	v_mov_b32_e32 v145, v199
	v_pk_add_f32 v[2:3], v[16:17], v[30:31]
	v_mov_b32_e32 v16, v75
	v_mov_b32_e32 v17, v18
	v_mov_b32_e32 v18, v59
	v_mov_b32_e32 v19, v20
	v_pk_add_f32 v[98:99], v[92:93], v[88:89] neg_lo:[0,1] neg_hi:[0,1]
	v_pk_add_f32 v[88:89], v[92:93], v[88:89]
	v_mul_f32_e32 v62, 0x3f3504f3, v4
	v_pk_add_f32 v[78:79], v[80:81], v[78:79] neg_lo:[0,1] neg_hi:[0,1]
	v_fmac_f32_e32 v67, 0x3f3504f3, v4
	v_pk_fma_f32 v[146:147], v[42:43], v[52:53], v[48:49] neg_lo:[0,0,1] neg_hi:[0,0,1]
	v_pk_fma_f32 v[42:43], v[42:43], v[52:53], v[142:143] op_sel:[0,0,1] op_sel_hi:[1,1,0]
	v_pk_add_f32 v[28:29], v[56:57], v[28:29]
	v_pk_add_f32 v[10:11], v[10:11], v[26:27]
	v_pk_add_f32 v[4:5], v[4:5], v[40:41]
	v_pk_add_f32 v[12:13], v[12:13], v[24:25]
	v_pk_add_f32 v[14:15], v[144:145], v[38:39]
	v_pk_add_f32 v[16:17], v[16:17], v[32:33]
	v_pk_add_f32 v[18:19], v[18:19], v[22:23]
	v_mov_b32_e32 v92, v98
	v_mov_b32_e32 v93, v89
	v_mov_b32_e32 v137, v73
	v_mov_b32_e32 v135, v79
	v_mov_b32_e32 v147, v43
	v_pk_fma_f32 v[42:43], v[44:45], v[68:69], v[46:47] neg_lo:[0,0,1] neg_hi:[0,0,1]
	v_pk_fma_f32 v[44:45], v[44:45], v[68:69], v[46:47]
	v_mov_b32_e32 v63, v187
	v_pk_add_f32 v[20:21], v[28:29], v[14:15]
	v_pk_add_f32 v[22:23], v[10:11], v[2:3]
	v_pk_add_f32 v[24:25], v[4:5], v[16:17]
	v_pk_add_f32 v[26:27], v[12:13], v[18:19]
	v_pk_mul_f32 v[130:131], v[92:93], v[88:89] op_sel:[0,1] op_sel_hi:[1,0]
	v_pk_mul_f32 v[136:137], v[136:137], s[26:27]
	v_mov_b32_e32 v43, v45
	v_pk_add_f32 v[44:45], v[134:135], v[62:63] neg_lo:[0,1] neg_hi:[0,1]
	v_pk_mul_f32 v[52:53], v[78:79], s[2:3]
	v_mov_b32_e32 v61, v81
	v_mov_b32_e32 v55, v76
	v_pk_add_f32 v[30:31], v[20:21], v[24:25] neg_lo:[0,1] neg_hi:[0,1]
	v_pk_add_f32 v[38:39], v[22:23], v[26:27] neg_lo:[0,1] neg_hi:[0,1]
	v_mov_b32_e32 v45, v53
	v_pk_add_f32 v[52:53], v[60:61], v[54:55]
	v_pk_add_f32 v[32:33], v[22:23], v[26:27]
	v_mov_b32_e32 v60, v30
	v_mov_b32_e32 v61, v22
	v_pk_mov_b32 v[22:23], v[38:39], v[26:27] op_sel:[1,0]
	v_mov_b32_e32 v131, v136
	v_mov_b32_e32 v136, v130
	v_mov_b32_e32 v74, v70
	v_pk_add_f32 v[22:23], v[60:61], v[22:23] neg_lo:[0,1] neg_hi:[0,1]
	v_pk_add_f32 v[60:61], v[130:131], v[136:137]
	v_pk_mul_f32 v[138:139], v[74:75], s[80:81] op_sel_hi:[1,0]
	v_pk_mul_f32 v[70:71], v[70:71], s[82:83]
	v_pk_add_f32 v[72:73], v[60:61], v[64:65] op_sel_hi:[1,0] neg_lo:[0,1] neg_hi:[0,1]
	v_mov_b32_e32 v186, v139
	v_mov_b32_e32 v71, v73
	v_pk_add_f32 v[72:73], v[70:71], v[186:187] neg_lo:[0,1] neg_hi:[0,1]
	v_pk_mul_f32 v[70:71], v[70:71], v[186:187]
	v_pk_mul_f32 v[128:129], v[126:127], v[126:127]
	v_pk_mul_f32 v[132:133], v[92:93], v[92:93]
	v_pk_add_f32 v[12:13], v[12:13], v[18:19] neg_lo:[0,1] neg_hi:[0,1]
	v_pk_add_f32 v[18:19], v[20:21], v[24:25]
	v_mov_b32_e32 v73, v71
	v_mov_b32_e32 v49, v44
	v_mov_b32_e32 v57, v72
	v_pk_fma_f32 v[140:141], v[74:75], s[80:81], v[138:139] op_sel:[0,0,1] op_sel_hi:[1,0,0] neg_lo:[0,0,1] neg_hi:[0,0,1]
	v_pk_add_f32 v[40:41], v[18:19], v[32:33]
	v_pk_add_f32 v[58:59], v[18:19], v[32:33] neg_lo:[0,1] neg_hi:[0,1]
	v_mov_b32_e32 v18, v128
	v_mov_b32_e32 v32, v129
	v_mov_b32_e32 v20, v132
	v_mov_b32_e32 v24, v133
	v_pk_add_f32 v[76:77], v[44:45], v[72:73] neg_lo:[0,1] neg_hi:[0,1]
	v_pk_add_f32 v[44:45], v[48:49], v[56:57]
	v_add_f32_e32 v142, v67, v140
	v_pk_add_f32 v[18:19], v[18:19], v[32:33] neg_lo:[0,1] neg_hi:[0,1]
	v_pk_add_f32 v[20:21], v[20:21], v[24:25] neg_lo:[0,1] neg_hi:[0,1]
	v_mov_b32_e32 v74, v7
	v_mov_b32_e32 v75, v64
	v_mov_b32_e32 v46, v44
	v_mov_b32_e32 v32, v58
	v_mov_b32_e32 v33, v120
	v_mul_f32_e32 v6, v19, v120
	v_pk_add_f32 v[26:27], v[38:39], v[30:31] op_sel:[1,0] op_sel_hi:[0,1]
	v_pk_add_f32 v[30:31], v[20:21], v[22:23] neg_lo:[0,1] neg_hi:[0,1]
	v_pk_add_f32 v[74:75], v[74:75], v[60:61]
	v_pk_add_f32 v[46:47], v[46:47], v[142:143] neg_lo:[0,1] neg_hi:[0,1]
	v_pk_add_f32 v[54:55], v[52:53], v[52:53] op_sel:[0,1] op_sel_hi:[1,0] neg_lo:[0,1] neg_hi:[0,1]
	v_pk_fma_f32 v[32:33], v[18:19], v[32:33], v[6:7] op_sel_hi:[1,1,0] neg_lo:[0,0,1] neg_hi:[0,0,1]
	v_mov_b32_e32 v27, v31
	v_mul_f32_e32 v6, v123, v31
	v_mov_b32_e32 v25, v51
	v_mov_b32_e32 v143, v47
	v_pk_mov_b32 v[50:51], v[50:51], v[52:53] op_sel:[1,0]
	v_mov_b32_e32 v52, v75
	v_pk_fma_f32 v[30:31], v[126:127], v[26:27], v[6:7] op_sel_hi:[1,1,0] neg_lo:[0,0,1] neg_hi:[0,0,1]
	v_mul_f32_e32 v6, v123, v26
	v_pk_add_f32 v[48:49], v[142:143], v[44:45]
	v_pk_add_f32 v[50:51], v[50:51], v[52:53]
	v_pk_fma_f32 v[26:27], v[124:125], v[26:27], v[6:7] op_sel_hi:[1,1,0]
	v_mov_b32_e32 v6, v7
	v_pk_add_f32 v[52:53], v[48:49], v[50:51] neg_lo:[0,1] neg_hi:[0,1]
	v_pk_add_f32 v[48:49], v[48:49], v[50:51]
	v_pk_mul_f32 v[64:65], v[6:7], v[60:61]
	v_mul_f32_e32 v6, v7, v49
	v_pk_mul_f32 v[58:59], v[120:121], v[58:59]
	v_mov_b32_e32 v62, v7
	v_mov_b32_e32 v63, v8
	v_pk_mul_f32 v[120:121], v[8:9], v[120:121] op_sel:[1,0] op_sel_hi:[0,0]
; #define FFT_HD __device__ __attribute__((always_inline))
; template <int R> FFT_HD inline void dft_fwd_reg(cf2 (&v)[1 << R]) {
;     constexpr int n = 1 << R;
; #pragma unroll
;     for (int s = 0; s < R; ++s) {
;         const int half = n >> (s + 1);
; #pragma unroll
;         for (int m = 0; m < n; ++m) {
;             if ((m & half) == 0) {
;                 const int ml = m & (half - 1), tk = ml * (16 / half);
;                 const cf2 a = v[m], b = v[m + half];
;                 v[m].x = a.x + b.x; v[m].y = a.y + b.y;
;                 const cf2 d = {a.x - b.x, a.y - b.y};
;                 if (tk == 0) v[m + half] = d;
;                 else if (tk == 8) { v[m + half].x = d.y; v[m + half].y = -d.x; }
;                 else { const cf2 w = {fc32(tk), -fs32(tk)}; v[m + half] = cmulf(d, w); }
;             }
;         }
;     }
; }
; template <int R, int F, bool CONJ> FFT_HD inline void tw_apply(cf2 (&v)[1 << R], cf2 pf, cf2 th) {
;     constexpr int j = fbrev(F, R);
;     v[j] = CONJ ? cmulcf(v[j], pf) : cmulf(v[j], pf);
;     if constexpr (2 * F < (1 << R)) {
;         const cf2 p2 = cmulf(pf, pf);
;         tw_apply<R, 2 * F, CONJ>(v, p2, th);
;         const cf2 p3 = cmulf(p2, th);
;         tw_apply<R, 2 * F + 1, CONJ>(v, p3, th);
;     }
; }
	v_pk_fma_f32 v[50:51], v[8:9], v[48:49], v[6:7] op_sel_hi:[1,1,0] neg_lo:[0,0,1] neg_hi:[0,0,1]
	v_mul_f32_e32 v6, v7, v48
	v_pk_fma_f32 v[58:59], v[18:19], v[18:19], v[58:59] op_sel:[1,0,0] op_sel_hi:[0,1,1]
	v_pk_fma_f32 v[126:127], v[8:9], v[18:19], v[120:121] op_sel_hi:[1,0,1] neg_lo:[0,0,1] neg_hi:[0,0,1]
	v_pk_fma_f32 v[18:19], v[8:9], v[18:19], v[120:121] op_sel_hi:[1,0,1]
	v_pk_fma_f32 v[6:7], v[62:63], v[48:49], v[6:7] op_sel_hi:[1,1,0]
	v_mul_f32_e32 v66, 0xbf3504f3, v79
	v_mul_f32_e32 v24, v8, v20
	v_mov_b32_e32 v65, v75
	v_pk_mov_b32 v[70:71], v[70:71], v[140:141] op_sel:[1,0]
	v_mov_b32_e32 v120, v126
	v_mov_b32_e32 v121, v19
	v_mov_b32_e32 v44, v54
	v_mul_f32_e32 v6, v19, v53
	v_pk_add_f32 v[66:67], v[66:67], v[70:71] neg_lo:[0,1] neg_hi:[0,1]
	v_pk_add_f32 v[24:25], v[24:25], v[64:65] neg_lo:[0,1] neg_hi:[0,1]
	v_pk_add_f32 v[44:45], v[46:47], v[44:45] neg_lo:[0,1] neg_hi:[0,1]
	v_pk_fma_f32 v[48:49], v[120:121], v[52:53], v[6:7] op_sel_hi:[1,1,0] neg_lo:[0,0,1] neg_hi:[0,0,1]
	v_pk_mov_b32 v[56:57], v[18:19], v[126:127] op_sel:[1,0]
	v_mul_f32_e32 v6, v19, v52
	v_pk_add_f32 v[64:65], v[42:43], v[66:67] neg_lo:[0,1] neg_hi:[0,1]
	v_pk_add_f32 v[70:71], v[146:147], v[76:77]
	v_pk_add_f32 v[78:79], v[146:147], v[76:77] neg_lo:[0,1] neg_hi:[0,1]
	v_pk_fma_f32 v[18:19], v[56:57], v[52:53], v[6:7] op_sel_hi:[1,1,0]
	v_pk_add_f32 v[46:47], v[46:47], v[54:55]
	v_pk_add_f32 v[52:53], v[44:45], v[24:25] neg_lo:[0,1] neg_hi:[0,1]
	v_mov_b32_e32 v147, v42
	v_mov_b32_e32 v77, v66
	v_mov_b32_e32 v116, v94
	v_mov_b32_e32 v117, v115
	v_pk_add_f32 v[80:81], v[42:43], v[66:67]
	v_mov_b32_e32 v122, v64
	v_pk_add_f32 v[124:125], v[78:79], v[64:65] neg_lo:[0,1] neg_hi:[0,1]
	v_mov_b32_e32 v47, v53
	v_mul_f32_e32 v6, v115, v53
	v_pk_add_f32 v[42:43], v[146:147], v[76:77]
	v_mov_b32_e32 v64, v71
	v_pk_mov_b32 v[118:119], v[114:115], v[94:95] op_sel:[1,0]
	v_pk_add_f32 v[2:3], v[10:11], v[2:3] neg_lo:[0,1] neg_hi:[0,1]
	v_pk_fma_f32 v[52:53], v[116:117], v[46:47], v[6:7] op_sel_hi:[1,1,0] neg_lo:[0,0,1] neg_hi:[0,0,1]
	v_mul_f32_e32 v6, v115, v46
	v_pk_add_f32 v[54:55], v[42:43], v[64:65]
	v_mul_f32_e32 v11, 0x3f3504f3, v2
	v_pk_add_f32 v[38:39], v[20:21], v[22:23]
	v_mov_b32_e32 v68, v20
	v_mov_b32_e32 v69, v60
	v_mul_f32_e32 v10, v8, v60
	v_pk_fma_f32 v[46:47], v[118:119], v[46:47], v[6:7] op_sel_hi:[1,1,0]
	v_mul_f32_e32 v6, v103, v55
	v_pk_fma_f32 v[68:69], v[62:63], v[68:69], v[10:11] op_sel_hi:[1,1,0]
	v_pk_fma_f32 v[56:57], v[110:111], v[54:55], v[6:7] op_sel_hi:[1,1,0] neg_lo:[0,0,1] neg_hi:[0,0,1]
	v_mul_f32_e32 v6, v103, v54
	v_pk_mul_f32 v[62:63], v[60:61], v[38:39] op_sel:[0,1] op_sel_hi:[1,0]
	v_pk_fma_f32 v[54:55], v[112:113], v[54:55], v[6:7] op_sel_hi:[1,1,0]
	v_pk_fma_f32 v[62:63], v[20:21], v[22:23], v[62:63] neg_lo:[0,0,1] neg_hi:[0,0,1]
	v_mov_b32_e32 v61, v20
	v_mov_b32_e32 v23, v39
	v_mul_f32_e32 v6, v60, v22
	v_pk_fma_f32 v[20:21], v[60:61], v[22:23], v[6:7] op_sel_hi:[1,1,0]
	v_pk_add_f32 v[22:23], v[44:45], v[24:25]
	v_mul_f32_e32 v2, 0x3f3504f3, v12
	v_pk_mul_f32 v[38:39], v[68:69], v[22:23] op_sel:[0,1] op_sel_hi:[1,0]
	v_pk_add_f32 v[14:15], v[28:29], v[14:15] neg_lo:[0,1] neg_hi:[0,1]
	v_fma_f32 v28, v3, s80, -v11
	v_pk_mul_f32 v[100:101], v[8:9], v[88:89] op_sel:[1,1] op_sel_hi:[0,1]
	v_mov_b32_e32 v123, v81
	v_pk_fma_f32 v[38:39], v[44:45], v[24:25], v[38:39] neg_lo:[0,0,1] neg_hi:[0,0,1]
	v_mov_b32_e32 v69, v24
	v_mov_b32_e32 v45, v23
	v_mul_f32_e32 v6, v68, v44
	v_mov_b32_e32 v29, v28
	v_fmac_f32_e32 v11, 0x3f3504f3, v3
	v_mov_b32_e32 v10, v28
	v_pk_add_f32 v[4:5], v[4:5], v[16:17] neg_lo:[0,1] neg_hi:[0,1]
	v_pk_fma_f32 v[2:3], v[12:13], s[82:83], v[2:3] op_sel:[1,0,0] op_sel_hi:[1,1,0] neg_lo:[0,0,1] neg_hi:[0,0,1]
	v_pk_fma_f32 v[104:105], v[8:9], v[98:99], v[100:101] op_sel_hi:[1,0,1] neg_lo:[0,0,1] neg_hi:[0,0,1]
	v_pk_fma_f32 v[100:101], v[8:9], v[98:99], v[100:101] op_sel_hi:[1,0,1]
	v_pk_add_f32 v[122:123], v[78:79], v[122:123]
	v_pk_fma_f32 v[22:23], v[68:69], v[44:45], v[6:7] op_sel_hi:[1,1,0]
	v_pk_add_f32 v[24:25], v[80:81], v[78:79] neg_lo:[0,1] neg_hi:[0,1]
	v_pk_add_f32 v[12:13], v[14:15], v[4:5] op_sel:[0,1] op_sel_hi:[1,0] neg_lo:[0,1] neg_hi:[0,1]
	v_pk_add_f32 v[16:17], v[14:15], v[4:5] op_sel:[0,1] op_sel_hi:[1,0]
	v_pk_add_f32 v[68:69], v[10:11], v[2:3]
	v_pk_mov_b32 v[4:5], v[4:5], v[28:29] op_sel:[1,0]
	v_mov_b32_e32 v15, v2
	v_pk_mul_f32 v[96:97], v[116:117], v[116:117]
	v_pk_mul_f32 v[94:95], v[94:95], v[116:117] op_sel_hi:[0,1]
	v_mov_b32_e32 v106, v104
	v_mov_b32_e32 v107, v101
	v_mov_b32_e32 v24, v122
	v_mul_f32_e32 v6, v101, v25
	v_mov_b32_e32 v16, v12
	v_pk_add_f32 v[10:11], v[10:11], v[2:3] neg_lo:[0,1] neg_hi:[0,1]
	v_pk_add_f32 v[2:3], v[4:5], v[14:15]
	v_mov_b32_e32 v12, v69
	v_pk_mov_b32 v[108:109], v[100:101], v[104:105] op_sel:[1,0]
	v_pk_fma_f32 v[44:45], v[106:107], v[24:25], v[6:7] op_sel_hi:[1,1,0] neg_lo:[0,0,1] neg_hi:[0,0,1]
	v_mul_f32_e32 v6, v101, v122
	v_pk_add_f32 v[4:5], v[2:3], v[12:13]
	v_mov_b32_e32 v12, v96
	v_mov_b32_e32 v28, v97
	v_mov_b32_e32 v29, v3
	v_mov_b32_e32 v3, v95
	v_mov_b32_e32 v94, v69
	v_pk_fma_f32 v[24:25], v[108:109], v[24:25], v[6:7] op_sel_hi:[1,1,0]
	v_mul_f32_e32 v6, v83, v5
	v_pk_add_f32 v[12:13], v[12:13], v[28:29] neg_lo:[0,1] neg_hi:[0,1]
	v_pk_add_f32 v[28:29], v[2:3], v[94:95] neg_lo:[0,1] neg_hi:[0,1]
	v_pk_add_f32 v[2:3], v[2:3], v[94:95]
	v_mov_b32_e32 v64, v42
	v_mov_b32_e32 v42, v71
	v_pk_fma_f32 v[14:15], v[86:87], v[4:5], v[6:7] op_sel_hi:[1,1,0] neg_lo:[0,0,1] neg_hi:[0,0,1]
	v_mul_f32_e32 v6, v83, v4
	v_pk_mul_f32 v[68:69], v[8:9], v[2:3] op_sel:[1,1] op_sel_hi:[0,1]
	v_pk_add_f32 v[42:43], v[64:65], v[42:43] neg_lo:[0,1] neg_hi:[0,1]
; #define FFT_HD __device__ __attribute__((always_inline))
; template <int R, int F, bool CONJ> FFT_HD inline void tw_apply(cf2 (&v)[1 << R], cf2 pf, cf2 th) {
;     constexpr int j = fbrev(F, R);
;     v[j] = CONJ ? cmulcf(v[j], pf) : cmulf(v[j], pf);
;     if constexpr (2 * F < (1 << R)) {
;         const cf2 p2 = cmulf(pf, pf);
;         tw_apply<R, 2 * F, CONJ>(v, p2, th);
;         const cf2 p3 = cmulf(p2, th);
;         tw_apply<R, 2 * F + 1, CONJ>(v, p3, th);
;     }
; }
; template <int R, int S> FFT_HD inline int grp_base(int grp) { return (grp / S) * (S << R) + (grp & (S - 1)); }
; template <int R, int S, class P> FFT_HD inline void grp_load(P X, int grp, cf2 (&v)[1 << R]) {
;     P Xb = X + fpad(grp_base<R, S>(grp));
; #pragma unroll
;     for (int m = 0; m < (1 << R); ++m) v[m] = Xb[m * S + ((m * S) >> 3)];
; }
; template <int R, int S, class P> FFT_HD inline void grp_store(P X, int grp, const cf2 (&v)[1 << R]) {
;     P Xb = X + fpad(grp_base<R, S>(grp));
; #pragma unroll
;     for (int m = 0; m < (1 << R); ++m) Xb[m * S + ((m * S) >> 3)] = v[m];
; }
	v_pk_fma_f32 v[4:5], v[84:85], v[4:5], v[6:7] op_sel_hi:[1,1,0]
	v_pk_fma_f32 v[72:73], v[8:9], v[12:13], v[68:69] op_sel_hi:[1,0,1] neg_lo:[0,0,1] neg_hi:[0,0,1]
	v_pk_fma_f32 v[68:69], v[8:9], v[12:13], v[68:69] op_sel_hi:[1,0,1]
	v_mov_b32_e32 v74, v72
	v_mov_b32_e32 v75, v69
	v_mul_f32_e32 v4, v69, v43
	v_pk_fma_f32 v[74:75], v[74:75], v[42:43], v[4:5] op_sel_hi:[1,1,0] neg_lo:[0,0,1] neg_hi:[0,0,1]
	v_pk_mov_b32 v[72:73], v[68:69], v[72:73] op_sel:[1,0]
	v_mul_f32_e32 v4, v69, v42
	v_mov_b32_e32 v29, v3
	v_pk_fma_f32 v[42:43], v[72:73], v[42:43], v[4:5] op_sel_hi:[1,1,0]
	v_mul_f32_e32 v4, v13, v3
	v_pk_fma_f32 v[68:69], v[12:13], v[28:29], v[4:5] op_sel_hi:[1,1,0] neg_lo:[0,0,1] neg_hi:[0,0,1]
	v_pk_mov_b32 v[72:73], v[2:3], v[12:13] op_sel:[1,0]
	v_mov_b32_e32 v29, v13
	v_mul_f32_e32 v2, v3, v28
	v_pk_mov_b32 v[90:91], v[88:89], v[98:99] op_sel:[1,0]
	v_pk_mul_f32 v[98:99], v[106:107], v[106:107]
	v_pk_mul_f32 v[104:105], v[106:107], v[100:101] op_sel:[0,1] op_sel_hi:[1,0]
	v_pk_add_f32 v[70:71], v[16:17], v[10:11] neg_lo:[0,1] neg_hi:[0,1]
	v_pk_add_f32 v[10:11], v[16:17], v[10:11]
	v_pk_fma_f32 v[2:3], v[72:73], v[28:29], v[2:3] op_sel_hi:[1,1,0]
	v_mov_b32_e32 v60, v98
	v_mov_b32_e32 v61, v104
	v_pk_mov_b32 v[64:65], v[98:99], v[104:105] op_sel:[1,0]
	v_mov_b32_e32 v12, v10
	v_mov_b32_e32 v13, v71
	v_mul_f32_e32 v2, v89, v71
	v_pk_add_f32 v[66:67], v[60:61], v[64:65] neg_lo:[0,1] neg_hi:[0,1]
	v_pk_add_f32 v[60:61], v[60:61], v[64:65]
	v_pk_fma_f32 v[28:29], v[92:93], v[12:13], v[2:3] op_sel_hi:[1,1,0] neg_lo:[0,0,1] neg_hi:[0,0,1]
	v_mul_f32_e32 v2, v89, v10
	v_mov_b32_e32 v64, v66
	v_mov_b32_e32 v65, v61
	v_mov_b32_e32 v16, v70
	v_mov_b32_e32 v17, v11
	v_pk_fma_f32 v[12:13], v[90:91], v[12:13], v[2:3] op_sel_hi:[1,1,0]
	v_mul_f32_e32 v2, v61, v11
	v_pk_fma_f32 v[10:11], v[64:65], v[16:17], v[2:3] op_sel_hi:[1,1,0] neg_lo:[0,0,1] neg_hi:[0,0,1]
	v_pk_mov_b32 v[64:65], v[60:61], v[66:67] op_sel:[1,0]
	v_mul_f32_e32 v2, v61, v70
	v_pk_mul_f32 v[60:61], v[8:9], v[60:61] op_sel:[1,1] op_sel_hi:[0,1]
	v_pk_fma_f32 v[16:17], v[64:65], v[16:17], v[2:3] op_sel_hi:[1,1,0]
	v_pk_fma_f32 v[64:65], v[8:9], v[66:67], v[60:61] op_sel_hi:[1,0,1] neg_lo:[0,0,1] neg_hi:[0,0,1]
	v_pk_fma_f32 v[8:9], v[8:9], v[66:67], v[60:61] op_sel_hi:[1,0,1]
	v_mov_b32_e32 v125, v123
	v_mov_b32_e32 v60, v64
	v_mov_b32_e32 v61, v9
	v_mul_f32_e32 v2, v9, v123
	v_pk_fma_f32 v[60:61], v[60:61], v[124:125], v[2:3] op_sel_hi:[1,1,0] neg_lo:[0,0,1] neg_hi:[0,0,1]
	v_pk_mov_b32 v[64:65], v[8:9], v[64:65] op_sel:[1,0]
	v_mul_f32_e32 v2, v9, v124
	v_pk_fma_f32 v[8:9], v[64:65], v[124:125], v[2:3] op_sel_hi:[1,1,0]
	v_mov_b32_e32 v33, v58
	v_mov_b32_e32 v31, v27
	v_mov_b32_e32 v63, v21
	v_mov_b32_e32 v15, v5
	v_mov_b32_e32 v69, v3
	v_mov_b32_e32 v29, v13
	v_mov_b32_e32 v11, v17
	v_mov_b32_e32 v51, v7
	v_mov_b32_e32 v49, v19
	v_mov_b32_e32 v53, v47
	v_mov_b32_e32 v39, v23
	v_mov_b32_e32 v57, v55
	v_mov_b32_e32 v75, v43
	v_mov_b32_e32 v45, v25
	v_mov_b32_e32 v61, v9
	s_movk_i32 s3, 0x200
	ds_write2st64_b64 v177, v[40:41], v[32:33] offset1:18
	ds_write2st64_b64 v177, v[30:31], v[62:63] offset0:36 offset1:54
	ds_write2st64_b64 v177, v[14:15], v[68:69] offset0:72 offset1:90
	ds_write2st64_b64 v177, v[28:29], v[10:11] offset0:108 offset1:126
	ds_write_b64 v178, v[50:51]
	ds_write_b64 v179, v[48:49]
	ds_write_b64 v180, v[52:53]
	ds_write_b64 v181, v[38:39]
	ds_write_b64 v182, v[56:57]
	ds_write_b64 v185, v[74:75]
	ds_write_b64 v189, v[44:45]
	ds_write_b64 v198, v[60:61]
	s_cbranch_vccz .LBB0_661
	s_waitcnt lgkmcnt(0)
	s_barrier
; #define FFT_HD __device__ __attribute__((always_inline))
; template <int R> FFT_HD inline void reg_fwd(cf2 (&v)[1 << R], cf2 th) { dft_fwd_reg<R>(v); tw_apply<R, 1, false>(v, th, th); }
; template <int R, int F, bool CONJ> FFT_HD inline void tw_apply(cf2 (&v)[1 << R], cf2 pf, cf2 th) {
;     constexpr int j = fbrev(F, R);
;     v[j] = CONJ ? cmulcf(v[j], pf) : cmulf(v[j], pf);
;     if constexpr (2 * F < (1 << R)) {
;         const cf2 p2 = cmulf(pf, pf);
;         tw_apply<R, 2 * F, CONJ>(v, p2, th);
;         const cf2 p3 = cmulf(p2, th);
;         tw_apply<R, 2 * F + 1, CONJ>(v, p3, th);
;     }
; }
; __device__ __forceinline__ void s_mid2(ldsc X, const cf2* TW, int tid) {
; #pragma unroll 1
;     for (int q = 0; q < 2; ++q) { const int grp = tid + 512 * q; cf2 v[16]; grp_load<4, 64>(X, grp, v); reg_fwd<4>(v, TW[(grp & 63) * 16]); grp_store<4, 64>(X, grp, v); }
	global_load_dwordx2 v[38:39], v[34:35], off
	s_mov_b32 s3, 0
	s_mov_b64 s[4:5], -1
	s_waitcnt vmcnt(0)
	v_pk_mul_f32 v[2:3], v[38:39], v[38:39] op_sel:[1,1] op_sel_hi:[0,1]
	v_pk_fma_f32 v[4:5], v[38:39], v[38:39], v[2:3] op_sel_hi:[0,1,1] neg_lo:[0,0,1] neg_hi:[0,0,1]
	v_pk_fma_f32 v[2:3], v[38:39], v[38:39], v[2:3] op_sel_hi:[0,1,1]
	v_pk_mov_b32 v[44:45], v[2:3], v[4:5] op_sel:[1,0]
	v_pk_mul_f32 v[6:7], v[38:39], v[2:3] op_sel:[1,1] op_sel_hi:[0,1]
	v_mov_b32_e32 v42, v4
	v_mov_b32_e32 v43, v3
	v_pk_mul_f32 v[2:3], v[2:3], v[44:45] op_sel:[1,0]
	v_pk_fma_f32 v[8:9], v[38:39], v[4:5], v[6:7] op_sel_hi:[1,0,1] neg_lo:[0,0,1] neg_hi:[0,0,1]
	v_pk_fma_f32 v[6:7], v[38:39], v[4:5], v[6:7] op_sel_hi:[1,0,1]
	v_pk_fma_f32 v[10:11], v[4:5], v[42:43], v[2:3] op_sel_hi:[0,1,1] neg_lo:[0,0,1] neg_hi:[0,0,1]
	v_pk_fma_f32 v[2:3], v[4:5], v[42:43], v[2:3] op_sel_hi:[0,1,1]
	v_pk_mov_b32 v[48:49], v[6:7], v[8:9] op_sel:[1,0]
	v_mov_b32_e32 v46, v8
	v_mov_b32_e32 v47, v7
	v_pk_mov_b32 v[52:53], v[2:3], v[10:11] op_sel:[1,0]
	v_pk_mul_f32 v[4:5], v[38:39], v[10:11] op_sel_hi:[1,0]
	v_pk_mul_f32 v[6:7], v[6:7], v[48:49] op_sel:[1,0]
	v_mov_b32_e32 v50, v10
	v_mov_b32_e32 v51, v3
	v_pk_mul_f32 v[12:13], v[2:3], v[52:53] op_sel:[1,0]
	v_pk_fma_f32 v[14:15], v[38:39], v[2:3], v[4:5] op_sel:[0,1,1] op_sel_hi:[1,1,0] neg_lo:[1,0,0] neg_hi:[1,0,0]
	v_pk_fma_f32 v[2:3], v[38:39], v[2:3], v[4:5] op_sel:[0,1,1] op_sel_hi:[1,1,0]
	v_pk_fma_f32 v[4:5], v[8:9], v[46:47], v[6:7] op_sel_hi:[0,1,1] neg_lo:[0,0,1] neg_hi:[0,0,1]
	v_pk_fma_f32 v[6:7], v[8:9], v[46:47], v[6:7] op_sel_hi:[0,1,1]
	v_pk_fma_f32 v[8:9], v[10:11], v[50:51], v[12:13] op_sel_hi:[0,1,1] neg_lo:[0,0,1] neg_hi:[0,0,1]
	v_pk_fma_f32 v[10:11], v[10:11], v[50:51], v[12:13] op_sel_hi:[0,1,1]
	v_pk_mov_b32 v[12:13], v[14:15], v[2:3] op_sel:[1,0]
	v_pk_mov_b32 v[58:59], v[6:7], v[4:5] op_sel:[1,0]
	v_pk_mul_f32 v[16:17], v[38:39], v[6:7] op_sel:[1,1] op_sel_hi:[0,1]
	v_mov_b32_e32 v54, v2
	v_mov_b32_e32 v55, v15
	v_mov_b32_e32 v56, v4
	v_mov_b32_e32 v57, v7
	v_mov_b32_e32 v61, v11
	v_pk_mov_b32 v[62:63], v[10:11], v[8:9] op_sel:[1,0]
	v_pk_mul_f32 v[10:11], v[38:39], v[10:11] op_sel:[1,1] op_sel_hi:[0,1]
	v_pk_mul_f32 v[2:3], v[2:3], v[12:13] op_sel_hi:[0,1]
	v_pk_mul_f32 v[6:7], v[6:7], v[58:59] op_sel:[1,0]
	v_pk_fma_f32 v[12:13], v[38:39], v[4:5], v[16:17] op_sel_hi:[1,0,1] neg_lo:[0,0,1] neg_hi:[0,0,1]
	v_pk_fma_f32 v[16:17], v[38:39], v[4:5], v[16:17] op_sel_hi:[1,0,1]
	v_mov_b32_e32 v60, v8
	v_pk_fma_f32 v[18:19], v[38:39], v[8:9], v[10:11] op_sel_hi:[1,0,1] neg_lo:[0,0,1] neg_hi:[0,0,1]
	v_pk_fma_f32 v[8:9], v[38:39], v[8:9], v[10:11] op_sel_hi:[1,0,1]
	v_pk_fma_f32 v[10:11], v[14:15], v[54:55], v[2:3] op_sel:[1,0,0] neg_lo:[0,0,1] neg_hi:[0,0,1]
	v_pk_fma_f32 v[2:3], v[14:15], v[54:55], v[2:3] op_sel:[1,0,0]
	v_pk_fma_f32 v[14:15], v[4:5], v[56:57], v[6:7] op_sel_hi:[0,1,1] neg_lo:[0,0,1] neg_hi:[0,0,1]
	v_pk_fma_f32 v[4:5], v[4:5], v[56:57], v[6:7] op_sel_hi:[0,1,1]
	v_pk_mov_b32 v[66:67], v[16:17], v[12:13] op_sel:[1,0]
	v_mov_b32_e32 v64, v12
	v_mov_b32_e32 v65, v17
	v_mov_b32_e32 v70, v2
	v_pk_mul_f32 v[2:3], v[38:39], v[2:3] op_sel:[1,0] op_sel_hi:[0,0]
	v_mov_b32_e32 v73, v5
	v_pk_mov_b32 v[74:75], v[4:5], v[14:15] op_sel:[1,0]
	v_pk_mul_f32 v[4:5], v[38:39], v[4:5] op_sel:[1,1] op_sel_hi:[0,1]
	v_pk_mul_f32 v[6:7], v[16:17], v[66:67] op_sel:[1,0]
	v_mov_b32_e32 v69, v9
	v_mov_b32_e32 v71, v11
	v_mov_b32_e32 v72, v14
	v_pk_mov_b32 v[76:77], v[8:9], v[18:19] op_sel:[1,0]
	v_pk_fma_f32 v[8:9], v[38:39], v[10:11], v[2:3] op_sel:[0,1,0] neg_lo:[0,0,1] neg_hi:[0,0,1]
	v_pk_fma_f32 v[2:3], v[38:39], v[10:11], v[2:3] op_sel:[0,1,0]
	v_pk_fma_f32 v[10:11], v[38:39], v[14:15], v[4:5] op_sel_hi:[1,0,1] neg_lo:[0,0,1] neg_hi:[0,0,1]
	v_pk_fma_f32 v[4:5], v[38:39], v[14:15], v[4:5] op_sel_hi:[1,0,1]
	v_pk_fma_f32 v[14:15], v[12:13], v[64:65], v[6:7] op_sel_hi:[0,1,1] neg_lo:[0,0,1] neg_hi:[0,0,1]
	v_pk_fma_f32 v[6:7], v[12:13], v[64:65], v[6:7] op_sel_hi:[0,1,1]
	v_mov_b32_e32 v83, v7
	v_pk_mov_b32 v[84:85], v[6:7], v[14:15] op_sel:[1,0]
	v_pk_mul_f32 v[6:7], v[38:39], v[6:7] op_sel:[1,1] op_sel_hi:[0,1]
	v_mov_b32_e32 v79, v3
	v_mov_b32_e32 v81, v5
	v_pk_mov_b32 v[86:87], v[4:5], v[10:11] op_sel:[1,0]
	v_pk_mov_b32 v[88:89], v[2:3], v[8:9] op_sel:[1,0]
	v_pk_fma_f32 v[2:3], v[38:39], v[14:15], v[6:7] op_sel_hi:[1,0,1] neg_lo:[0,0,1] neg_hi:[0,0,1]
	v_pk_fma_f32 v[4:5], v[38:39], v[14:15], v[6:7] op_sel_hi:[1,0,1]
	v_pk_mov_b32 v[40:41], v[38:39], v[38:39] op_sel:[1,0]
	v_mov_b32_e32 v68, v18
	v_mov_b32_e32 v78, v8
	v_mov_b32_e32 v80, v10
	v_mov_b32_e32 v82, v14
	v_mov_b32_e32 v90, v2
	v_mov_b32_e32 v91, v5
	v_pk_mov_b32 v[92:93], v[4:5], v[2:3] op_sel:[1,0]

; #define FFT_HD __device__ __attribute__((always_inline))
; template <class BP> FFT_HD inline void fm_load(BP dst, int tid, const float* a, const float* b, bool full) {
; #pragma unroll
;     for (int i = 0; i < 4; ++i) { const int t = tid + 512 * i;
;         *(FFT_LDSU*)(dst + (t & 63) * FM_PITCH + (t >> 6) * 4) = fm_pack(a[t], b[t]);
;         const int t2 = t + 2048;
;         *(FFT_LDSU*)(dst + (t2 & 63) * FM_PITCH + (t2 >> 6) * 4) = full ? fm_pack(a[t2], b[t2]) : 0u; }
; }
; __device__ __forceinline__ void hyena_conv_p(const float* HYT, float* ZOUT, const float* FILT, const unsigned char* fmtab, LAS unsigned char* lds, int vb, int nb, int tid_in) {
;     ...
;     for (int u = vb; u < 1024; u += nb) {
;         int tid = tid_in; asm volatile("" : "+v"(tid));
;         const int lane = tid & 63, w = __builtin_amdgcn_readfirstlane(tid >> 6);
;         const int c = u;
;         const float* hv = HYT + (size_t)c * MTOK; float* zo = ZOUT + (size_t)c * MTOK; const float* hx1 = HYT + (size_t)(1024 + c) * MTOK; const float* hx2 = HYT + (size_t)(2048 + c) * MTOK;
;         const float* f0 = FILT + (size_t)c * 4096; const float* f1 = FILT + (size_t)(1024 + c) * 4096;
;         int cur = 0; f32x4 acc[4];
;         cplx K0[4][2], K1[4][2];
;         __syncthreads();
;         fm_load(lds, tid, f0, f1, true);
;         __syncthreads();
;         fm_sweep(lds, cur, w, lane, C, acc);
.LBB0_690:
	v_mov_b32_e32 v36, v1
	s_ashr_i32 s43, s42, 31
	v_readfirstlane_b32 s6, v36
	s_ashr_i32 s6, s6, 6
	s_lshl_b64 s[30:31], s[42:43], 14
	s_add_u32 s30, s3, s30
	v_ashrrev_i32_e32 v37, 31, v36
	s_addc_u32 s31, s28, s31
	v_lshlrev_b64 v[34:35], 2, v[36:37]
	v_lshl_add_u64 v[38:39], s[30:31], 0, v[34:35]
	s_mov_b32 s7, 0x1001000
	v_add_co_u32_e32 v42, vcc, s7, v38
	s_movk_i32 s7, 0x3000
	s_nop 0
	v_addc_co_u32_e32 v43, vcc, 0, v39, vcc
	v_add_co_u32_e32 v44, vcc, s48, v38
	s_nop 1
	v_addc_co_u32_e32 v45, vcc, 0, v39, vcc
	v_add_co_u32_e32 v46, vcc, s7, v38
	s_mov_b32 s7, 0x1002000
	s_nop 0
	v_addc_co_u32_e32 v47, vcc, 0, v39, vcc
	v_add_co_u32_e32 v48, vcc, s7, v38
	s_mov_b32 s7, 0x1003000
	s_nop 0
	v_addc_co_u32_e32 v49, vcc, 0, v39, vcc
	v_add_co_u32_e32 v66, vcc, s7, v38
	s_nop 0
	v_addc_co_u32_e32 v67, vcc, 0, v39, vcc
	global_load_dword v37, v[46:47], off offset:-4096
	global_load_dword v70, v[66:67], off offset:-4096
	s_mov_b64 s[30:31], 0x1000000
	v_lshl_add_u64 v[40:41], v[38:39], 0, s[30:31]
	v_add_co_u32_e32 v68, vcc, s25, v38
	v_and_b32_e32 v78, 63, v36
	s_nop 0
	v_addc_co_u32_e32 v69, vcc, 0, v39, vcc
	global_load_dword v71, v[38:39], off
	global_load_dword v72, v[42:43], off offset:-4096
	s_nop 0
	global_load_dword v38, v[38:39], off offset:2048
	s_nop 0
	global_load_dword v39, v[40:41], off offset:2048
	s_nop 0
	global_load_dword v40, v[44:45], off offset:2048
	global_load_dword v41, v[48:49], off offset:2048
	s_nop 0
	global_load_dword v44, v[68:69], off
	global_load_dword v45, v[42:43], off
	global_load_dword v48, v[46:47], off
	global_load_dword v49, v[66:67], off
	s_nop 0
	global_load_dword v68, v[68:69], off offset:2048
	s_nop 0
	global_load_dword v66, v[66:67], off offset:2048
	s_nop 0
	global_load_dword v46, v[46:47], off offset:2048
	s_nop 0
	global_load_dword v42, v[42:43], off offset:2048
	v_ashrrev_i32_e32 v43, 4, v36
	v_add_u32_e32 v47, 0x800, v36
	s_movk_i32 s7, 0x110
	v_add_u32_e32 v67, 0x200, v36
	v_add_u32_e32 v69, 0xa00, v36
	v_add_u32_e32 v73, 0x400, v36
	v_mad_u32_u24 v75, v78, s7, 0
	v_and_b32_e32 v43, -4, v43
	v_ashrrev_i32_e32 v47, 4, v47
	v_ashrrev_i32_e32 v67, 4, v67
	v_ashrrev_i32_e32 v69, 4, v69
	v_ashrrev_i32_e32 v73, 4, v73
	v_add_u32_e32 v236, v75, v43
	v_and_b32_e32 v43, -4, v47
	v_and_b32_e32 v47, -4, v67
	v_and_b32_e32 v67, -4, v69
	v_and_b32_e32 v69, -4, v73
	v_add_u32_e32 v237, v75, v43
	v_add_u32_e32 v238, v75, v47
	v_add_u32_e32 v239, v75, v67
	v_add_u32_e32 v240, v75, v69
	v_add_u32_e32 v74, 0xc00, v36
	v_ashrrev_i32_e32 v74, 4, v74
	v_and_b32_e32 v73, -4, v74
	v_add_u32_e32 v241, v75, v73
	v_and_b32_e32 v142, 15, v36
	v_or_b32_e32 v90, 48, v78
	v_lshlrev_b32_e32 v130, 3, v36
	s_movk_i32 s47, 0x1ffe
	s_cmp_lt_i32 s6, 4
	s_cselect_b64 s[50:51], -1, 0
	s_cmp_gt_i32 s6, 3
	s_cselect_b64 s[54:55], -1, 0
	s_mul_i32 s43, s45, 0x18000
	v_mul_u32_u24_e32 v208, 0x110, v90
	s_mul_hi_i32 s31, s45, 0x18000
	v_lshl_add_u64 v[118:119], s[14:15], 0, v[34:35]
	v_and_b32_e32 v143, 0x180, v130
	s_mul_i32 s30, s46, 0x18000
	v_mul_u32_u24_e32 v246, 0x110, v142
	s_waitcnt vmcnt(12)
	v_cvt_pk_f16_f32 v43, v71, v72
	s_waitcnt vmcnt(10)
	v_cvt_pk_f16_f32 v38, v38, v39
	v_cvt_pk_f16_f32 v37, v37, v70
	s_waitcnt vmcnt(8)
	v_cvt_pk_f16_f32 v39, v40, v41
	s_waitcnt vmcnt(6)
	v_cvt_pk_f16_f32 v40, v44, v45
	s_barrier
	ds_write_b32 v236, v43
	ds_write_b32 v237, v37
	ds_write_b32 v238, v38
	ds_write_b32 v239, v39
	ds_write_b32 v240, v40
	v_add_u32_e32 v37, 0x600, v36
	v_ashrrev_i32_e32 v37, 4, v37
	v_and_b32_e32 v37, -4, v37
	v_add_u32_e32 v242, v75, v37
	v_add_u32_e32 v37, 0xe00, v36
	v_ashrrev_i32_e32 v37, 4, v37
	v_and_b32_e32 v37, -4, v37
	v_add_u32_e32 v243, v75, v37
	v_and_b32_e32 v37, 48, v36
	s_waitcnt vmcnt(4)
	v_cvt_pk_f16_f32 v41, v48, v49
	s_waitcnt vmcnt(0)
	v_cvt_pk_f16_f32 v38, v68, v42
	v_add_u32_e32 v244, 0, v37
	ds_write_b32 v241, v41
	ds_write_b32 v242, v38
	v_cvt_pk_f16_f32 v38, v46, v66
	v_mad_u32_u24 v37, v142, s7, v244
	ds_write_b32 v243, v38
	s_waitcnt lgkmcnt(0)
	s_barrier
	ds_read_b128 v[38:41], v37
	ds_read_b128 v[42:45], v37 offset:64
	ds_read_b128 v[46:49], v37 offset:4352
	ds_read_b128 v[66:69], v37 offset:4416
	ds_read_b128 v[70:73], v37 offset:8704
	ds_read_b128 v[74:77], v37 offset:8768
	v_mad_u32_u24 v91, v90, s7, v244
	s_waitcnt lgkmcnt(5)
	v_mfma_f32_16x16x32_f16 v[38:41], v[26:29], v[38:41], 0
	ds_read_b128 v[78:81], v91
	ds_read_b128 v[82:85], v91 offset:64
	s_waitcnt lgkmcnt(5)
	v_mfma_f32_16x16x32_f16 v[46:49], v[26:29], v[46:49], 0
	s_waitcnt lgkmcnt(3)
	v_mfma_f32_16x16x32_f16 v[70:73], v[26:29], v[70:73], 0
	s_waitcnt lgkmcnt(1)
	v_mfma_f32_16x16x32_f16 v[78:81], v[26:29], v[78:81], 0
	v_mfma_f32_16x16x32_f16 v[38:41], v[18:21], v[42:45], v[38:41]
	v_mfma_f32_16x16x32_f16 v[42:45], v[18:21], v[66:69], v[46:49]
	v_mfma_f32_16x16x32_f16 v[46:49], v[18:21], v[74:77], v[70:73]
	s_nop 2
	ds_read_b128 v[70:73], v37 offset:128
	ds_read_b128 v[74:77], v37 offset:192
	s_waitcnt lgkmcnt(2)
	v_mfma_f32_16x16x32_f16 v[66:69], v[18:21], v[82:85], v[78:81]
	s_waitcnt lgkmcnt(1)
	v_mfma_f32_16x16x32_f16 v[38:41], v[22:25], v[70:73], v[38:41]
	ds_read_b128 v[70:73], v37 offset:4480
	ds_read_b128 v[78:81], v37 offset:4544
	s_waitcnt lgkmcnt(1)
	v_mfma_f32_16x16x32_f16 v[42:45], v[22:25], v[70:73], v[42:45]
	ds_read_b128 v[70:73], v37 offset:8832
	ds_read_b128 v[82:85], v37 offset:8896
	s_waitcnt lgkmcnt(1)
	v_mfma_f32_16x16x32_f16 v[46:49], v[22:25], v[70:73], v[46:49]
	ds_read_b128 v[70:73], v91 offset:128
	ds_read_b128 v[86:89], v91 offset:192
	s_waitcnt lgkmcnt(1)
; #define LAS __attribute__((address_space(3)))
; FFT_HD inline int fm_boff(int lane, int nt, int ks) { return (16 * nt + (lane & 15)) * FM_PITCH + (16 * ks + 4 * (lane >> 4)) * 4; }
; __device__ __forceinline__ void fm_matmul(ldsb buf, int lane, const FmConst& C, f32x4 (&acc)[4]) {
; #pragma unroll
;     for (int nt = 0; nt < 4; ++nt) acc[nt] = (f32x4){0.f, 0.f, 0.f, 0.f};
; #pragma unroll
;     for (int ks = 0; ks < 4; ++ks)
; #pragma unroll
;         for (int nt = 0; nt < 4; ++nt) acc[nt] = __builtin_amdgcn_mfma_f32_16x16x32_f16(C.afr[ks], *(const LAS h8v*)(buf + fm_boff(lane, nt, ks)), acc[nt], 0, 0, 0);
; }
; __device__ __forceinline__ void fm_sweep(ldsb lds, int& cur, int w, int lane, const FmConst& C, f32x4 (&acc)[4]) {
;     fm_matmul(lds + cur * FM_BUF, lane, C, acc);
; #pragma unroll
;     for (int nt = 0; nt < 4; ++nt) { const float a[4] = {acc[nt].x, acc[nt].y, acc[nt].z, acc[nt].w}; fm_e1(lds + (cur ^ 1) * FM_BUF, w, lane, nt, a, C.tw[nt]); }
;     __syncthreads(); cur ^= 1;
;     fm_matmul(lds + cur * FM_BUF, lane, C, acc);
; __device__ __forceinline__ void hyena_conv_p(const float* HYT, float* ZOUT, const float* FILT, const unsigned char* fmtab, LAS unsigned char* lds, int vb, int nb, int tid_in) {
;     ...
;         fm_sweep(lds, cur, w, lane, C, acc);
; #pragma unroll
;         for (int nt = 0; nt < 4; ++nt) { const float a[4] = {acc[nt].x, acc[nt].y, acc[nt].z, acc[nt].w}; fm_e2f(nmf, w, lane, nt, a); }
;         __syncthreads(); cur ^= 1;
	v_mfma_f32_16x16x32_f16 v[66:69], v[22:25], v[70:73], v[66:69]
	v_lshrrev_b32_e32 v70, 3, v36
	v_and_b32_e32 v70, 6, v70
	v_lshl_or_b32 v92, s6, 3, v70
	v_mfma_f32_16x16x32_f16 v[38:41], v[30:33], v[74:77], v[38:41]
	v_lshlrev_b32_e32 v70, 2, v36
	v_and_b32_e32 v70, 60, v70
	v_add_u32_e32 v75, 0, v70
	v_mfma_f32_16x16x32_f16 v[42:45], v[30:33], v[78:81], v[42:45]
	v_mul_lo_u32 v74, v92, s7
	s_nop 2
	v_pk_mul_f32 v[70:71], v[58:59], v[38:39]
	v_lshrrev_b32_e32 v36, 1, v36
	v_pk_fma_f32 v[72:73], v[10:11], v[38:39], v[70:71] op_sel:[0,0,1] op_sel_hi:[1,1,0] neg_lo:[0,0,1] neg_hi:[0,0,1]
	v_pk_fma_f32 v[38:39], v[10:11], v[38:39], v[70:71] op_sel:[0,0,1] op_sel_hi:[1,1,0]
	v_add_u32_e32 v73, v75, v74
	v_cvt_pk_f16_f32 v72, v72, v39
	v_pk_mul_f32 v[38:39], v[60:61], v[40:41]
	v_mfma_f32_16x16x32_f16 v[46:49], v[30:33], v[82:85], v[46:49]
	v_fma_f32 v70, v12, v40, -v39
	v_fma_f32 v71, v13, v41, -v38
	v_pk_fma_f32 v[38:39], v[12:13], v[40:41], v[38:39] op_sel:[0,0,1] op_sel_hi:[1,1,0]
	v_add_u32_e32 v245, 0x4400, v73
	v_cvt_pk_f16_f32 v70, v70, v39
	v_pk_mul_f32 v[38:39], v[50:51], v[42:43]
	s_waitcnt lgkmcnt(0)
	v_mfma_f32_16x16x32_f16 v[66:69], v[30:33], v[86:89], v[66:69]
	v_fma_f32 v40, v6, v42, -v39
	v_fma_f32 v41, v7, v43, -v38
	v_pk_fma_f32 v[38:39], v[6:7], v[42:43], v[38:39] op_sel:[0,0,1] op_sel_hi:[1,1,0]
	v_and_b32_e32 v36, 24, v36
	v_cvt_pk_f16_f32 v38, v40, v39
	ds_write2_b32 v245, v72, v38 offset1:16
	v_pk_mul_f32 v[38:39], v[52:53], v[44:45]
	s_mul_hi_i32 s7, s46, 0x18000
	v_pk_fma_f32 v[40:41], v[8:9], v[44:45], v[38:39] op_sel:[0,0,1] op_sel_hi:[1,1,0] neg_lo:[0,0,1] neg_hi:[0,0,1]
	v_pk_fma_f32 v[38:39], v[8:9], v[44:45], v[38:39] op_sel:[0,0,1] op_sel_hi:[1,1,0]
	s_nop 0
	v_cvt_pk_f16_f32 v38, v40, v39
	ds_write2_b32 v245, v70, v38 offset0:68 offset1:84
	v_pk_mul_f32 v[38:39], v[54:55], v[46:47]
	s_nop 0
	v_pk_fma_f32 v[40:41], v[2:3], v[46:47], v[38:39] op_sel:[0,0,1] op_sel_hi:[1,1,0] neg_lo:[0,0,1] neg_hi:[0,0,1]
	v_pk_fma_f32 v[38:39], v[2:3], v[46:47], v[38:39] op_sel:[0,0,1] op_sel_hi:[1,1,0]
	s_nop 0
	v_cvt_pk_f16_f32 v42, v40, v39
	v_pk_mul_f32 v[38:39], v[56:57], v[48:49]
	s_nop 0
	v_pk_fma_f32 v[40:41], v[4:5], v[48:49], v[38:39] op_sel:[0,0,1] op_sel_hi:[1,1,0] neg_lo:[0,0,1] neg_hi:[0,0,1]
	v_pk_fma_f32 v[38:39], v[4:5], v[48:49], v[38:39] op_sel:[0,0,1] op_sel_hi:[1,1,0]
	s_nop 0
	v_cvt_pk_f16_f32 v43, v40, v39
	v_pk_mul_f32 v[38:39], v[62:63], v[66:67]
	s_nop 0
	v_pk_fma_f32 v[40:41], v[14:15], v[66:67], v[38:39] op_sel:[0,0,1] op_sel_hi:[1,1,0] neg_lo:[0,0,1] neg_hi:[0,0,1]
	v_pk_fma_f32 v[38:39], v[14:15], v[66:67], v[38:39] op_sel:[0,0,1] op_sel_hi:[1,1,0]
	s_nop 0
	v_cvt_pk_f16_f32 v38, v40, v39
	ds_write2_b32 v245, v42, v38 offset0:32 offset1:48
	v_pk_mul_f32 v[38:39], v[64:65], v[68:69]
	s_nop 0
	v_pk_fma_f32 v[40:41], v[16:17], v[68:69], v[38:39] op_sel:[0,0,1] op_sel_hi:[1,1,0] neg_lo:[0,0,1] neg_hi:[0,0,1]
	v_pk_fma_f32 v[38:39], v[16:17], v[68:69], v[38:39] op_sel:[0,0,1] op_sel_hi:[1,1,0]
	s_nop 0
	v_cvt_pk_f16_f32 v38, v40, v39
	ds_write2_b32 v245, v43, v38 offset0:100 offset1:116
	s_waitcnt lgkmcnt(0)
	s_barrier
	ds_read_b128 v[38:41], v37 offset:17408
	ds_read_b128 v[42:45], v37 offset:17472
	ds_read_b128 v[46:49], v37 offset:21760
	ds_read_b128 v[66:69], v37 offset:21824
	ds_read_b128 v[70:73], v37 offset:26112
	ds_read_b128 v[74:77], v37 offset:26176
	s_waitcnt lgkmcnt(5)
	v_mfma_f32_16x16x32_f16 v[38:41], v[26:29], v[38:41], 0
	ds_read_b128 v[78:81], v91 offset:17408
	ds_read_b128 v[82:85], v91 offset:17472
	s_waitcnt lgkmcnt(5)
	v_mfma_f32_16x16x32_f16 v[46:49], v[26:29], v[46:49], 0
	s_waitcnt lgkmcnt(3)
	v_mfma_f32_16x16x32_f16 v[70:73], v[26:29], v[70:73], 0
	s_waitcnt lgkmcnt(1)
	v_mfma_f32_16x16x32_f16 v[78:81], v[26:29], v[78:81], 0
	v_mfma_f32_16x16x32_f16 v[38:41], v[18:21], v[42:45], v[38:41]
	v_mfma_f32_16x16x32_f16 v[42:45], v[18:21], v[66:69], v[46:49]
	v_mfma_f32_16x16x32_f16 v[46:49], v[18:21], v[74:77], v[70:73]
	s_nop 2
	ds_read_b128 v[70:73], v37 offset:17536
	ds_read_b128 v[74:77], v37 offset:17600
	s_waitcnt lgkmcnt(2)
	v_mfma_f32_16x16x32_f16 v[66:69], v[18:21], v[82:85], v[78:81]
	s_waitcnt lgkmcnt(1)
	v_mfma_f32_16x16x32_f16 v[38:41], v[22:25], v[70:73], v[38:41]
	ds_read_b128 v[70:73], v37 offset:21888
	ds_read_b128 v[78:81], v37 offset:21952
	s_waitcnt lgkmcnt(1)
	v_mfma_f32_16x16x32_f16 v[42:45], v[22:25], v[70:73], v[42:45]
	ds_read_b128 v[70:73], v37 offset:26240
	ds_read_b128 v[82:85], v37 offset:26304
	v_and_b32_e32 v37, 0x78, v130
	s_waitcnt lgkmcnt(1)
	v_mfma_f32_16x16x32_f16 v[46:49], v[22:25], v[70:73], v[46:49]
	ds_read_b128 v[70:73], v91 offset:17536
	ds_read_b128 v[86:89], v91 offset:17600
	s_waitcnt lgkmcnt(1)
	v_mfma_f32_16x16x32_f16 v[66:69], v[22:25], v[70:73], v[66:69]
	v_lshlrev_b32_e32 v70, 9, v92
	v_add3_u32 v37, 0, v37, v70
	v_add_u32_e32 v37, 0x8800, v37
	v_mfma_f32_16x16x32_f16 v[38:41], v[30:33], v[74:77], v[38:41]
	v_mfma_f32_16x16x32_f16 v[42:45], v[30:33], v[78:81], v[42:45]
	v_mfma_f32_16x16x32_f16 v[46:49], v[30:33], v[82:85], v[46:49]
	s_waitcnt lgkmcnt(0)
	v_mfma_f32_16x16x32_f16 v[66:69], v[30:33], v[86:89], v[66:69]
	s_nop 4
	ds_write2_b64 v37, v[38:39], v[42:43] offset1:16
	ds_write2_b64 v37, v[40:41], v[44:45] offset0:64 offset1:80
	s_nop 0
	ds_write2_b64 v37, v[46:47], v[66:67] offset0:32 offset1:48
	ds_write2_b64 v37, v[48:49], v[68:69] offset0:96 offset1:112
	v_lshlrev_b32_e32 v37, 6, v92
	v_or_b32_e32 v42, v37, v142
	v_mul_lo_u32 v43, v42, s47
	v_and_b32_e32 v39, 0x1ffe, v43
	v_lshl_add_u32 v38, v42, 3, 0
	v_lshl_add_u32 v44, v39, 2, 0
	v_add_u32_e32 v43, 0x7ff80, v43
	s_waitcnt lgkmcnt(0)
	s_barrier
; #define FFT_HD __device__ __attribute__((always_inline))
; template <class FP> FFT_HD inline void fm_split(FP nmf, int w, int lane, int nt, cplx (&K0)[2], cplx (&K1)[2]) {
;     const int g = lane >> 4, k1 = 16 * nt + (lane & 15), k2 = 8 * w + 2 * g; const float s = 0.5f / 4096.0f;
; #pragma unroll
;     for (int q = 0; q < 2; ++q) { const int f = k1 + 64 * (k2 + q), f2 = (4096 - f) & 4095;
;         const float zr = nmf[2 * f], zi = nmf[2 * f + 1], wr = nmf[2 * f2], wi = nmf[2 * f2 + 1];
;         K0[q].x = s * (zr + wr); K0[q].y = s * (zi - wi); K1[q].x = s * (zi + wi); K1[q].y = s * (wr - zr); }
; }
; __device__ __forceinline__ void hyena_conv_p(const float* HYT, float* ZOUT, const float* FILT, const unsigned char* fmtab, LAS unsigned char* lds, int vb, int nb, int tid_in) {
;     ...
; #pragma unroll
;         for (int nt = 0; nt < 4; ++nt) fm_split(nmf, w, lane, nt, K0[nt], K1[nt]);
	ds_read2st64_b64 v[38:41], v38 offset0:68 offset1:69
	ds_read_b64 v[44:45], v44 offset:34816
	v_and_b32_e32 v43, 0x1ffe, v43
	v_lshl_add_u32 v43, v43, 2, 0
	ds_read_b64 v[46:47], v43 offset:34816
	v_or_b32_e32 v43, 16, v142
	s_waitcnt lgkmcnt(1)
	v_pk_add_f32 v[48:49], v[38:39], v[44:45]
	v_pk_add_f32 v[66:67], v[38:39], v[44:45] neg_lo:[0,1] neg_hi:[0,1]
	v_pk_add_f32 v[38:39], v[44:45], v[38:39] neg_lo:[0,1] neg_hi:[0,1]
	s_waitcnt lgkmcnt(0)
	v_pk_add_f32 v[44:45], v[40:41], v[46:47] neg_lo:[0,1] neg_hi:[0,1]
	v_mov_b32_e32 v39, v49
	v_pk_mul_f32 v[68:69], v[38:39], s[86:87] op_sel_hi:[1,0]
	v_pk_add_f32 v[38:39], v[40:41], v[46:47]
	v_pk_add_f32 v[40:41], v[46:47], v[40:41] neg_lo:[0,1] neg_hi:[0,1]
	v_mov_b32_e32 v44, v38
	v_pk_mul_f32 v[70:71], v[44:45], s[86:87] op_sel_hi:[1,0]
	v_or_b32_e32 v44, v37, v43
	v_mul_lo_u32 v45, v44, s47
	v_and_b32_e32 v38, 0x1ffe, v45
	v_mov_b32_e32 v41, v39
	v_lshl_add_u32 v37, v44, 3, 0
	v_lshl_add_u32 v46, v38, 2, 0
	v_pk_mul_f32 v[72:73], v[40:41], s[86:87] op_sel_hi:[1,0]
	ds_read2st64_b64 v[38:41], v37 offset0:68 offset1:69
	ds_read_b64 v[46:47], v46 offset:34816
	v_add_u32_e32 v37, 0x7ff80, v45
	v_and_b32_e32 v37, 0x1ffe, v37
	v_lshl_add_u32 v37, v37, 2, 0
	v_mov_b32_e32 v66, v48
	ds_read_b64 v[48:49], v37 offset:34816
	s_waitcnt lgkmcnt(1)
	v_pk_add_f32 v[76:77], v[38:39], v[46:47]
	v_pk_add_f32 v[74:75], v[38:39], v[46:47] neg_lo:[0,1] neg_hi:[0,1]
	v_pk_add_f32 v[38:39], v[46:47], v[38:39] neg_lo:[0,1] neg_hi:[0,1]
	v_mov_b32_e32 v74, v76
	v_mov_b32_e32 v39, v77
	v_pk_mul_f32 v[76:77], v[38:39], s[86:87] op_sel_hi:[1,0]
	s_waitcnt lgkmcnt(0)
	v_pk_add_f32 v[38:39], v[40:41], v[48:49]
	v_pk_add_f32 v[46:47], v[40:41], v[48:49] neg_lo:[0,1] neg_hi:[0,1]
	v_pk_add_f32 v[40:41], v[48:49], v[40:41] neg_lo:[0,1] neg_hi:[0,1]
	v_mov_b32_e32 v46, v38
	v_pk_mul_f32 v[78:79], v[46:47], s[86:87] op_sel_hi:[1,0]
	v_or_b32_e32 v46, 32, v42
	v_mul_lo_u32 v45, v46, s47
	v_mov_b32_e32 v41, v39
	v_lshl_add_u32 v37, v46, 3, 0
	v_and_b32_e32 v38, 0x1ffe, v45
	v_pk_mul_f32 v[80:81], v[40:41], s[86:87] op_sel_hi:[1,0]
	v_lshl_add_u32 v47, v38, 2, 0
	ds_read2st64_b64 v[38:41], v37 offset0:68 offset1:69
	ds_read_b64 v[48:49], v47 offset:34816
	v_add_u32_e32 v37, 0x7ff80, v45
	v_and_b32_e32 v37, 0x1ffe, v37
	v_lshl_add_u32 v37, v37, 2, 0
	ds_read_b64 v[88:89], v37 offset:34816
	s_waitcnt lgkmcnt(1)
	v_pk_add_f32 v[84:85], v[38:39], v[48:49]
	v_pk_add_f32 v[82:83], v[38:39], v[48:49] neg_lo:[0,1] neg_hi:[0,1]
	v_pk_add_f32 v[38:39], v[48:49], v[38:39] neg_lo:[0,1] neg_hi:[0,1]
	v_mov_b32_e32 v82, v84
	v_mov_b32_e32 v39, v85
	v_pk_mul_f32 v[84:85], v[38:39], s[86:87] op_sel_hi:[1,0]
	s_waitcnt lgkmcnt(0)
	v_pk_add_f32 v[38:39], v[40:41], v[88:89]
	v_pk_add_f32 v[48:49], v[40:41], v[88:89] neg_lo:[0,1] neg_hi:[0,1]
	v_pk_add_f32 v[40:41], v[88:89], v[40:41] neg_lo:[0,1] neg_hi:[0,1]
	v_mov_b32_e32 v48, v38
	v_pk_mul_f32 v[86:87], v[48:49], s[86:87] op_sel_hi:[1,0]
	v_or_b32_e32 v48, 48, v42
	v_mul_lo_u32 v45, v48, s47
	v_mov_b32_e32 v41, v39
	v_lshl_add_u32 v37, v48, 3, 0
	v_and_b32_e32 v38, 0x1ffe, v45
	v_pk_mul_f32 v[88:89], v[40:41], s[86:87] op_sel_hi:[1,0]
	v_lshl_add_u32 v47, v38, 2, 0
	ds_read2st64_b64 v[38:41], v37 offset0:68 offset1:69
	ds_read_b64 v[94:95], v47 offset:34816
	v_add_u32_e32 v37, 0x7ff80, v45
	v_and_b32_e32 v37, 0x1ffe, v37
	v_lshl_add_u32 v37, v37, 2, 0
	ds_read_b64 v[100:101], v37 offset:34816
	s_lshl_b32 s47, s6, 5
	s_waitcnt lgkmcnt(1)
	v_pk_add_f32 v[96:97], v[38:39], v[94:95]
	v_pk_add_f32 v[90:91], v[38:39], v[94:95] neg_lo:[0,1] neg_hi:[0,1]
	v_pk_add_f32 v[38:39], v[94:95], v[38:39] neg_lo:[0,1] neg_hi:[0,1]
	s_add_i32 s47, s47, 0
	v_mov_b32_e32 v39, v97
	v_mov_b32_e32 v45, v183
	v_mov_b32_e32 v47, v183
	v_mov_b32_e32 v49, v183
	s_add_u32 s56, s29, s43
	v_mov_b32_e32 v90, v96
	v_pk_mul_f32 v[94:95], v[38:39], s[86:87] op_sel_hi:[1,0]
	s_waitcnt lgkmcnt(0)
; #define FFT_HD __device__ __attribute__((always_inline))
; FFT_HD inline unsigned fm_tidx(int w, int lane, int nt, int q) { return (unsigned)(16 * nt + (lane & 15) + 64 * (8 * w + 2 * (lane >> 4) + q)); }
; template <class FP> FFT_HD inline void fm_split(FP nmf, int w, int lane, int nt, cplx (&K0)[2], cplx (&K1)[2]) {
;     const int g = lane >> 4, k1 = 16 * nt + (lane & 15), k2 = 8 * w + 2 * g; const float s = 0.5f / 4096.0f;
; #pragma unroll
;     for (int q = 0; q < 2; ++q) { const int f = k1 + 64 * (k2 + q), f2 = (4096 - f) & 4095;
;         const float zr = nmf[2 * f], zi = nmf[2 * f + 1], wr = nmf[2 * f2], wi = nmf[2 * f2 + 1];
;         K0[q].x = s * (zr + wr); K0[q].y = s * (zi - wi); K1[q].x = s * (zi + wi); K1[q].y = s * (wr - zr); }
; }
; __device__ __forceinline__ void hyena_conv_p(const float* HYT, float* ZOUT, const float* FILT, const unsigned char* fmtab, LAS unsigned char* lds, int vb, int nb, int tid_in) {
;     ...
; #pragma unroll 1
;         for (int pr = 0; pr < 4; ++pr) {
;             const float* va = hv + pr * 4096; const float* x1a = hx1 + pr * 4096; const float* x2a = hx2 + pr * 4096; float* oa = zo + pr * 4096;
;             __syncthreads();
;             fm_load(lds + cur * FM_BUF, tid, va, va + 2048, false);
;             float ga[4][2], gb[4][2];
;             if (w < 4) {
; #pragma unroll
;                 for (int nt = 0; nt < 4; ++nt)
; #pragma unroll
;                     for (int q = 0; q < 2; ++q) { const unsigned t = fm_tidx(w, lane, nt, q); ga[nt][q] = x1a[t]; gb[nt][q] = x1a[2048u + t]; } }
	v_pk_add_f32 v[38:39], v[40:41], v[100:101]
	v_pk_add_f32 v[96:97], v[40:41], v[100:101] neg_lo:[0,1] neg_hi:[0,1]
	v_pk_add_f32 v[40:41], v[100:101], v[40:41] neg_lo:[0,1] neg_hi:[0,1]
	v_add_u32_e32 v247, s47, v36
	v_add_u32_e32 v36, 0x800, v44
	v_lshlrev_b64 v[34:35], 2, v[48:49]
	s_addc_u32 s57, s44, s31
	v_lshlrev_b64 v[46:47], 2, v[46:47]
	v_lshlrev_b64 v[44:45], 2, v[44:45]
	v_mov_b32_e32 v41, v39
	v_mul_u32_u24_e32 v209, 0x110, v43
	v_mov_b32_e32 v43, v183
	v_lshl_add_u64 v[120:121], s[56:57], 0, v[34:35]
	v_lshl_add_u64 v[122:123], s[56:57], 0, v[46:47]
	v_lshl_add_u64 v[124:125], s[56:57], 0, v[44:45]
	s_add_u32 s56, s8, s43
	v_mov_b32_e32 v96, v38
	v_pk_mul_f32 v[100:101], v[40:41], s[86:87] op_sel_hi:[1,0]
	v_add_u32_e32 v182, 0x800, v42
	v_add_u32_e32 v38, 0x820, v42
	v_add_u32_e32 v40, 0x830, v42
	v_lshlrev_b64 v[42:43], 2, v[42:43]
	s_addc_u32 s57, s9, s31
	v_lshl_add_u64 v[126:127], s[56:57], 0, v[42:43]
	s_add_u32 s56, s64, s43
	s_addc_u32 s57, s65, s31
	s_lshl_b32 s6, s6, 9
	s_add_i32 s31, s6, 0x840
	v_lshlrev_b64 v[48:49], 2, v[182:183]
	v_or3_b32 v182, s31, v143, v142
	s_add_i32 s31, s6, 0x850
	v_lshlrev_b64 v[202:203], 2, v[182:183]
	v_or3_b32 v182, s31, v143, v142
	s_add_i32 s31, s6, 0x860
	v_lshlrev_b64 v[206:207], 2, v[182:183]
	v_or3_b32 v182, s31, v143, v142
	s_addk_i32 s6, 0x870
	v_mov_b32_e32 v37, v183
	v_mov_b32_e32 v39, v183
	v_mov_b32_e32 v41, v183
	v_lshlrev_b64 v[178:179], 2, v[182:183]
	v_or3_b32 v182, s6, v143, v142
	v_lshlrev_b64 v[36:37], 2, v[36:37]
	v_lshlrev_b64 v[38:39], 2, v[38:39]
	v_lshlrev_b64 v[40:41], 2, v[40:41]
	v_lshlrev_b64 v[174:175], 2, v[182:183]
	v_lshl_add_u64 v[128:129], s[56:57], 0, v[48:49]
	v_lshl_add_u64 v[130:131], s[56:57], 0, v[202:203]
	v_lshl_add_u64 v[132:133], s[56:57], 0, v[36:37]
	v_lshl_add_u64 v[134:135], s[56:57], 0, v[206:207]
	v_lshl_add_u64 v[136:137], s[56:57], 0, v[38:39]
	v_lshl_add_u64 v[138:139], s[56:57], 0, v[178:179]
	v_lshl_add_u64 v[140:141], s[56:57], 0, v[40:41]
	v_lshl_add_u64 v[142:143], s[56:57], 0, v[174:175]
	s_add_u32 s56, s29, s30
	s_addc_u32 s57, s44, s7
	v_lshl_add_u64 v[144:145], s[56:57], 0, v[34:35]
	v_lshl_add_u64 v[146:147], s[56:57], 0, v[46:47]
	v_lshl_add_u64 v[148:149], s[56:57], 0, v[44:45]
	s_add_u32 s56, s8, s30
	s_addc_u32 s57, s9, s7
	s_add_u32 s6, s64, s30
	v_pk_mul_f32 v[90:91], v[90:91], s[86:87] op_sel_hi:[1,0]
	v_pk_mul_f32 v[96:97], v[96:97], s[86:87] op_sel_hi:[1,0]
	s_addc_u32 s7, s65, s7
	v_pk_mul_f32 v[66:67], v[66:67], s[86:87] op_sel_hi:[1,0]
	v_pk_mul_f32 v[74:75], v[74:75], s[86:87] op_sel_hi:[1,0]
	v_pk_mul_f32 v[82:83], v[82:83], s[86:87] op_sel_hi:[1,0]
	v_pk_mov_b32 v[92:93], v[90:91], v[90:91] op_sel:[1,0]
	v_pk_mov_b32 v[98:99], v[96:97], v[96:97] op_sel:[1,0]
	v_pk_mov_b32 v[102:103], v[72:73], v[72:73] op_sel:[1,0]
	v_pk_mov_b32 v[104:105], v[68:69], v[68:69] op_sel:[1,0]
	v_pk_mov_b32 v[106:107], v[80:81], v[80:81] op_sel:[1,0]
	v_pk_mov_b32 v[108:109], v[76:77], v[76:77] op_sel:[1,0]
	v_pk_mov_b32 v[110:111], v[88:89], v[88:89] op_sel:[1,0]
	v_pk_mov_b32 v[112:113], v[84:85], v[84:85] op_sel:[1,0]
	v_pk_mov_b32 v[114:115], v[100:101], v[100:101] op_sel:[1,0]
	v_pk_mov_b32 v[116:117], v[94:95], v[94:95] op_sel:[1,0]
	v_lshl_add_u64 v[150:151], s[56:57], 0, v[42:43]
	v_lshl_add_u64 v[152:153], s[6:7], 0, v[48:49]
	v_lshl_add_u64 v[154:155], s[6:7], 0, v[202:203]
	v_lshl_add_u64 v[156:157], s[6:7], 0, v[36:37]
	v_lshl_add_u64 v[158:159], s[6:7], 0, v[206:207]
	v_lshl_add_u64 v[160:161], s[6:7], 0, v[38:39]
	v_lshl_add_u64 v[162:163], s[6:7], 0, v[178:179]
	v_lshl_add_u64 v[164:165], s[6:7], 0, v[40:41]
	v_lshl_add_u64 v[166:167], s[6:7], 0, v[174:175]
	v_lshl_add_u64 v[168:169], s[16:17], 0, v[34:35]
	v_lshl_add_u64 v[170:171], s[16:17], 0, v[46:47]
	v_lshl_add_u64 v[172:173], s[16:17], 0, v[44:45]
	v_lshl_add_u64 v[174:175], s[36:37], 0, v[174:175]
	v_lshl_add_u64 v[176:177], s[36:37], 0, v[40:41]
	v_lshl_add_u64 v[178:179], s[36:37], 0, v[178:179]
	v_lshl_add_u64 v[180:181], s[36:37], 0, v[38:39]
	v_lshl_add_u64 v[198:199], s[36:37], 0, v[42:43]
	v_lshl_add_u64 v[200:201], s[36:37], 0, v[48:49]
	v_lshl_add_u64 v[202:203], s[36:37], 0, v[202:203]
	v_lshl_add_u64 v[204:205], s[36:37], 0, v[36:37]
	v_lshl_add_u64 v[206:207], s[36:37], 0, v[206:207]
	s_mov_b64 s[56:57], 0
	v_add_u32_e32 v182, v244, v208
	v_add_u32_e32 v248, v247, v209
	s_branch .LBB0_692

; #define FFT_HD __device__ __attribute__((always_inline))
; FFT_HD inline unsigned fm_tidx(int w, int lane, int nt, int q) { return (unsigned)(16 * nt + (lane & 15) + 64 * (8 * w + 2 * (lane >> 4) + q)); }
; template <class BP> FFT_HD inline void fm_load(BP dst, int tid, const float* a, const float* b, bool full) {
; #pragma unroll
;     for (int i = 0; i < 4; ++i) { const int t = tid + 512 * i;
;         *(FFT_LDSU*)(dst + (t & 63) * FM_PITCH + (t >> 6) * 4) = fm_pack(a[t], b[t]);
;         const int t2 = t + 2048;
;         *(FFT_LDSU*)(dst + (t2 & 63) * FM_PITCH + (t2 >> 6) * 4) = full ? fm_pack(a[t2], b[t2]) : 0u; }
; }
; __device__ __forceinline__ void hyena_conv_p(const float* HYT, float* ZOUT, const float* FILT, const unsigned char* fmtab, LAS unsigned char* lds, int vb, int nb, int tid_in) {
;     ...
;         for (int pr = 0; pr < 4; ++pr) {
;             const float* va = hv + pr * 4096; const float* x1a = hx1 + pr * 4096; const float* x2a = hx2 + pr * 4096; float* oa = zo + pr * 4096;
;             __syncthreads();
;             fm_load(lds + cur * FM_BUF, tid, va, va + 2048, false);
;             float ga[4][2], gb[4][2];
;             if (w < 4) {
; #pragma unroll
;                 for (int nt = 0; nt < 4; ++nt)
; #pragma unroll
;                     for (int q = 0; q < 2; ++q) { const unsigned t = fm_tidx(w, lane, nt, q); ga[nt][q] = x1a[t]; gb[nt][q] = x1a[2048u + t]; } }
.LBB0_692:
	v_lshl_add_u64 v[34:35], v[118:119], 0, s[56:57]
	s_mov_b32 s6, 0x66200000
	v_add_co_u32_e32 v36, vcc, s6, v34
	s_mov_b32 s6, 0x66201000
	s_nop 0
	v_addc_co_u32_e32 v37, vcc, 0, v35, vcc
	v_add_co_u32_e32 v38, vcc, s6, v34
	s_mov_b32 s6, 0x66202000
	s_nop 0
	v_addc_co_u32_e32 v39, vcc, 0, v35, vcc
	v_add_co_u32_e32 v40, vcc, s6, v34
	s_nop 1
	v_addc_co_u32_e32 v41, vcc, 0, v35, vcc
	global_load_dword v42, v[38:39], off offset:-4096
	global_load_dword v43, v[40:41], off
	v_add_co_u32_e32 v34, vcc, 0x66203000, v34
	global_load_dword v36, v[36:37], off offset:2048
	s_nop 0
	global_load_dword v37, v[40:41], off offset:2048
	v_addc_co_u32_e32 v35, vcc, 0, v35, vcc
	s_andn2_b64 vcc, exec, s[50:51]
	global_load_dword v212, v[38:39], off
	global_load_dword v213, v[34:35], off
	global_load_dword v214, v[38:39], off offset:2048
	global_load_dword v215, v[34:35], off offset:2048
	s_waitcnt vmcnt(6)
	v_cvt_pk_f16_f32 v42, v42, v43
	s_barrier
	ds_write_b32 v236, v42
	ds_write_b32 v237, v183
	s_waitcnt vmcnt(4)
	v_cvt_pk_f16_f32 v36, v36, v37
	ds_write_b32 v238, v36
	ds_write_b32 v239, v183
	s_waitcnt vmcnt(2)
	v_cvt_pk_f16_f32 v36, v212, v213
	ds_write_b32 v240, v36
	ds_write_b32 v241, v183
	s_waitcnt vmcnt(0)
	v_cvt_pk_f16_f32 v34, v214, v215
	ds_write_b32 v242, v34
	ds_write_b32 v243, v183
	v_cndmask_b32_e64 v34, 0, 1, s[50:51]
	v_cmp_ne_u32_e64 s[6:7], 1, v34
	s_cbranch_vccnz .LBB0_694
	v_lshl_add_u64 v[34:35], v[126:127], 0, s[56:57]
	v_add_co_u32_e32 v34, vcc, 0x66200000, v34
	v_lshl_add_u64 v[36:37], v[128:129], 0, s[56:57]
	s_nop 0
	v_addc_co_u32_e32 v35, vcc, 0, v35, vcc
	global_load_dword v185, v[34:35], off
	global_load_dword v189, v[36:37], off
	global_load_dword v186, v[34:35], off offset:256
	v_lshl_add_u64 v[36:37], v[130:131], 0, s[56:57]
	global_load_dword v192, v[36:37], off
	global_load_dword v190, v[34:35], off offset:64
	v_lshl_add_u64 v[36:37], v[132:133], 0, s[56:57]
	global_load_dword v225, v[36:37], off
	v_lshl_add_u64 v[36:37], v[124:125], 0, s[56:57]
	global_load_dword v226, v[36:37], off
	v_lshl_add_u64 v[36:37], v[134:135], 0, s[56:57]
	global_load_dword v228, v[36:37], off
	global_load_dword v227, v[34:35], off offset:128
	v_lshl_add_u64 v[36:37], v[136:137], 0, s[56:57]
	global_load_dword v229, v[36:37], off
	v_lshl_add_u64 v[36:37], v[122:123], 0, s[56:57]
	global_load_dword v230, v[36:37], off
	v_lshl_add_u64 v[36:37], v[138:139], 0, s[56:57]
	global_load_dword v231, v[36:37], off
	global_load_dword v232, v[34:35], off offset:192
	v_lshl_add_u64 v[34:35], v[140:141], 0, s[56:57]
	global_load_dword v233, v[34:35], off
	v_lshl_add_u64 v[34:35], v[120:121], 0, s[56:57]
	global_load_dword v234, v[34:35], off
	v_lshl_add_u64 v[34:35], v[142:143], 0, s[56:57]
	global_load_dword v235, v[34:35], off
